# attention epilogue rewritten: all gate-z loads issued up front (were serialized with vmcnt(0)), row-sum-of-squares reductions batched via DPP
# speedup vs baseline: 1.0264x; 1.0264x over previous
.LBB0_421:
	s_and_b32 s1, s53, 0x3fffffc0
	s_lshl_b32 s1, s1, 2
	s_waitcnt vmcnt(0)
	s_barrier
	s_add_i32 s44, s1, 0
	s_add_i32 s44, s44, 0x1e000
	s_cmp_lg_u32 0, -1
	s_cselect_b32 s30, 0, 0
	s_add_i32 s1, s30, 0x12000
	v_add_u32_e32 v156, s1, v209
	ds_read_b128 v[64:67], v156 offset:0
	ds_read_b128 v[68:71], v156 offset:0x3000
	v_add_u32_e32 v157, s1, v210
	ds_read_b128 v[148:151], v157 offset:0
	ds_read_b128 v[152:155], v157 offset:0x3000
	v_add_u32_e32 v174, s1, v211
	ds_read_b128 v[182:185], v174 offset:0
	ds_read_b128 v[230:233], v174 offset:0x3000
	s_waitcnt lgkmcnt(4)
	v_add_u32_e32 v175, s1, v212
	s_setprio 1
	v_mfma_f32_32x32x16_bf16 v[80:95], v[64:67], v[140:143], 0
	v_mfma_f32_32x32x16_bf16 v[64:79], v[68:71], v[140:143], 0
	s_setprio 0
	ds_read_b128 v[140:143], v175 offset:0
	ds_read_b128 v[234:237], v175 offset:0x3000
	s_waitcnt lgkmcnt(4)
	s_setprio 1
	v_mfma_f32_32x32x16_bf16 v[80:95], v[148:151], v[136:139], v[80:95]
	v_mfma_f32_32x32x16_bf16 v[64:79], v[152:155], v[136:139], v[64:79]
	s_setprio 0
	ds_read_b128 v[136:139], v156 offset:0x80
	ds_read_b128 v[148:151], v156 offset:0x3080
	s_waitcnt lgkmcnt(4)
	s_setprio 1
	v_mfma_f32_32x32x16_bf16 v[80:95], v[182:185], v[132:135], v[80:95]
	v_mfma_f32_32x32x16_bf16 v[64:79], v[230:233], v[132:135], v[64:79]
	s_setprio 0
	ds_read_b128 v[132:135], v157 offset:0x80
	ds_read_b128 v[152:155], v157 offset:0x3080
	s_waitcnt lgkmcnt(4)
	s_setprio 1
	v_mfma_f32_32x32x16_bf16 v[80:95], v[140:143], v[128:131], v[80:95]
	v_mfma_f32_32x32x16_bf16 v[64:79], v[234:237], v[128:131], v[64:79]
	s_setprio 0
	ds_read_b128 v[128:131], v174 offset:0x80
	ds_read_b128 v[140:143], v174 offset:0x3080
	s_waitcnt lgkmcnt(4)
	s_setprio 1
	v_mfma_f32_32x32x16_bf16 v[80:95], v[136:139], v[124:127], v[80:95]
	v_mfma_f32_32x32x16_bf16 v[64:79], v[148:151], v[124:127], v[64:79]
	s_setprio 0
	ds_read_b128 v[124:127], v175 offset:0x80
	ds_read_b128 v[136:139], v175 offset:0x3080
	s_waitcnt lgkmcnt(4)
	s_setprio 1
	v_mfma_f32_32x32x16_bf16 v[80:95], v[132:135], v[120:123], v[80:95]
	v_mfma_f32_32x32x16_bf16 v[64:79], v[152:155], v[120:123], v[64:79]
	s_setprio 0
	ds_read_b128 v[120:123], v156 offset:0x100
	ds_read_b128 v[132:135], v156 offset:0x3100
	s_waitcnt lgkmcnt(4)
	s_setprio 1
	v_mfma_f32_32x32x16_bf16 v[80:95], v[128:131], v[116:119], v[80:95]
	v_mfma_f32_32x32x16_bf16 v[64:79], v[140:143], v[116:119], v[64:79]
	s_setprio 0
	ds_read_b128 v[116:119], v157 offset:0x100
	ds_read_b128 v[128:131], v157 offset:0x3100
	s_waitcnt lgkmcnt(4)
	s_setprio 1
	v_mfma_f32_32x32x16_bf16 v[80:95], v[124:127], v[112:115], v[80:95]
	v_mfma_f32_32x32x16_bf16 v[64:79], v[136:139], v[112:115], v[64:79]
	s_setprio 0
	ds_read_b128 v[112:115], v174 offset:0x100
	ds_read_b128 v[124:127], v174 offset:0x3100
	s_waitcnt lgkmcnt(4)
	s_setprio 1
	v_mfma_f32_32x32x16_bf16 v[80:95], v[120:123], v[108:111], v[80:95]
	v_mfma_f32_32x32x16_bf16 v[64:79], v[132:135], v[108:111], v[64:79]
	s_setprio 0
	ds_read_b128 v[108:111], v175 offset:0x100
	ds_read_b128 v[120:123], v175 offset:0x3100
	s_waitcnt lgkmcnt(4)
	s_setprio 1
	v_mfma_f32_32x32x16_bf16 v[80:95], v[116:119], v[104:107], v[80:95]
	v_mfma_f32_32x32x16_bf16 v[64:79], v[128:131], v[104:107], v[64:79]
	s_setprio 0
	s_waitcnt lgkmcnt(2)
	s_setprio 1
	v_mfma_f32_32x32x16_bf16 v[80:95], v[112:115], v[100:103], v[80:95]
	v_mfma_f32_32x32x16_bf16 v[64:79], v[124:127], v[100:103], v[64:79]
	s_setprio 0
	s_waitcnt lgkmcnt(0)
	s_setprio 1
	v_mfma_f32_32x32x16_bf16 v[80:95], v[108:111], v[96:99], v[80:95]
	v_mfma_f32_32x32x16_bf16 v[64:79], v[120:123], v[96:99], v[64:79]
	s_setprio 0
	v_add_f32_e32 v96, 0, v224
	v_add_f32_e32 v96, v227, v96
	v_add_f32_e32 v96, v222, v96
	v_add_f32_e32 v96, v229, v96
	v_add_f32_e32 v96, v225, v96
	v_add_f32_e32 v96, v228, v96
	v_add_f32_e32 v96, v223, v96
	v_add_f32_e32 v96, v226, v96
	v_add_f32_e32 v96, v219, v96
	v_add_f32_e32 v96, v221, v96
	v_add_f32_e32 v96, v217, v96
	v_add_f32_e32 v96, v220, v96
	v_exp_f32_e32 v97, v172
	v_add_f32_e32 v96, v215, v96
	v_exp_f32_e32 v99, v173
	v_add_f32_e32 v96, v218, v96
	v_exp_f32_e32 v109, v170
	v_add_f32_e32 v96, v214, v96
	v_exp_f32_e32 v110, v171
	v_add_f32_e32 v96, v216, v96
	v_exp_f32_e32 v111, v168
	v_add_f32_e32 v96, v97, v96
	v_exp_f32_e32 v112, v169
	v_add_f32_e32 v96, v99, v96
	v_exp_f32_e32 v113, v164
	v_add_f32_e32 v96, v109, v96
	v_exp_f32_e32 v114, v165
	v_add_f32_e32 v96, v110, v96
	v_exp_f32_e32 v115, v166
	v_add_f32_e32 v96, v111, v96
	v_exp_f32_e32 v116, v167
	v_add_f32_e32 v96, v112, v96
	v_exp_f32_e32 v117, v162
	v_add_f32_e32 v96, v113, v96
	v_exp_f32_e32 v118, v163
	v_add_f32_e32 v96, v114, v96
	v_exp_f32_e32 v119, v160
	v_add_f32_e32 v96, v115, v96
	v_exp_f32_e32 v120, v161
	v_add_f32_e32 v96, v116, v96
	v_exp_f32_e32 v121, v158
	v_add_f32_e32 v96, v117, v96
	v_exp_f32_e32 v122, v159
	v_add_f32_e32 v96, v118, v96
	v_add_f32_e32 v96, v119, v96
	v_add_f32_e32 v96, v120, v96
	v_add_f32_e32 v96, v121, v96
	v_add_f32_e32 v96, v122, v96
	v_mov_b32_e32 v98, v96
	s_nop 1
	v_permlane32_swap_b32_e32 v96, v98
	v_cvt_pk_bf16_f32 v100, v224, v227
	v_cvt_pk_bf16_f32 v101, v222, v229
	v_cvt_pk_bf16_f32 v102, v225, v228
	v_cvt_pk_bf16_f32 v103, v223, v226
	v_cvt_pk_bf16_f32 v104, v219, v221
	v_cvt_pk_bf16_f32 v105, v217, v220
	v_cvt_pk_bf16_f32 v106, v215, v218
	v_cvt_pk_bf16_f32 v107, v214, v216
	v_cvt_pk_bf16_f32 v108, v97, v99
	v_cvt_pk_bf16_f32 v109, v109, v110
	v_cvt_pk_bf16_f32 v110, v111, v112
	v_cvt_pk_bf16_f32 v111, v113, v114
	v_cvt_pk_bf16_f32 v112, v115, v116
	v_cvt_pk_bf16_f32 v113, v117, v118
	v_cvt_pk_bf16_f32 v114, v119, v120
	v_cvt_pk_bf16_f32 v115, v121, v122
	s_nop 0
	v_permlane32_swap_b32_e32 v100, v102
	v_permlane32_swap_b32_e32 v101, v103
	v_permlane32_swap_b32_e32 v104, v106
	v_permlane32_swap_b32_e32 v105, v107
	v_permlane32_swap_b32_e32 v108, v110
	v_permlane32_swap_b32_e32 v109, v111
	v_permlane32_swap_b32_e32 v112, v114
	v_permlane32_swap_b32_e32 v113, v115
	ds_read_b64_tr_b16 v[116:117], v208 offset:0
	ds_read_b64_tr_b16 v[118:119], v208 offset:0x800
	ds_read_b64_tr_b16 v[120:121], v208 offset:0x1000
	ds_read_b64_tr_b16 v[122:123], v208 offset:0x1800
	ds_read_b64_tr_b16 v[124:125], v208 offset:0x2000
	ds_read_b64_tr_b16 v[126:127], v208 offset:0x2800
	ds_read_b64_tr_b16 v[128:129], v208 offset:0x3000
	ds_read_b64_tr_b16 v[130:131], v208 offset:0x3800
	ds_read_b64_tr_b16 v[132:133], v208 offset:0x200
	ds_read_b64_tr_b16 v[134:135], v208 offset:0xa00
	ds_read_b64_tr_b16 v[136:137], v208 offset:0x1200
	ds_read_b64_tr_b16 v[138:139], v208 offset:0x1a00
	ds_read_b64_tr_b16 v[140:141], v208 offset:0x2200
	ds_read_b64_tr_b16 v[142:143], v208 offset:0x2a00
	ds_read_b64_tr_b16 v[148:149], v208 offset:0x3200
	ds_read_b64_tr_b16 v[150:151], v208 offset:0x3a00
	s_waitcnt lgkmcnt(8)
	s_nop 0
	v_mfma_f32_32x32x16_bf16 v[48:63], v[100:103], v[116:119], v[48:63]
	v_mfma_f32_32x32x16_bf16 v[48:63], v[104:107], v[120:123], v[48:63]
	v_mfma_f32_32x32x16_bf16 v[48:63], v[108:111], v[124:127], v[48:63]
	v_mfma_f32_32x32x16_bf16 v[48:63], v[112:115], v[128:131], v[48:63]
	ds_read_b64_tr_b16 v[116:117], v208 offset:0x400
	ds_read_b64_tr_b16 v[118:119], v208 offset:0xc00
	ds_read_b64_tr_b16 v[120:121], v208 offset:0x1400
	ds_read_b64_tr_b16 v[122:123], v208 offset:0x1c00
	ds_read_b64_tr_b16 v[124:125], v208 offset:0x2400
	ds_read_b64_tr_b16 v[126:127], v208 offset:0x2c00
	ds_read_b64_tr_b16 v[128:129], v208 offset:0x3400
	ds_read_b64_tr_b16 v[130:131], v208 offset:0x3c00
	s_waitcnt lgkmcnt(8)
	v_mfma_f32_32x32x16_bf16 v[32:47], v[100:103], v[132:135], v[32:47]
	v_mfma_f32_32x32x16_bf16 v[32:47], v[104:107], v[136:139], v[32:47]
	v_mfma_f32_32x32x16_bf16 v[32:47], v[108:111], v[140:143], v[32:47]
	v_mfma_f32_32x32x16_bf16 v[32:47], v[112:115], v[148:151], v[32:47]
	ds_read_b64_tr_b16 v[132:133], v208 offset:0x600
	ds_read_b64_tr_b16 v[134:135], v208 offset:0xe00
	ds_read_b64_tr_b16 v[136:137], v208 offset:0x1600
	ds_read_b64_tr_b16 v[138:139], v208 offset:0x1e00
	ds_read_b64_tr_b16 v[140:141], v208 offset:0x2600
	ds_read_b64_tr_b16 v[142:143], v208 offset:0x2e00
	ds_read_b64_tr_b16 v[148:149], v208 offset:0x3600
	ds_read_b64_tr_b16 v[150:151], v208 offset:0x3e00
	s_waitcnt lgkmcnt(8)
	v_mfma_f32_32x32x16_bf16 v[16:31], v[100:103], v[116:119], v[16:31]
	v_mfma_f32_32x32x16_bf16 v[16:31], v[104:107], v[120:123], v[16:31]
	v_mfma_f32_32x32x16_bf16 v[16:31], v[108:111], v[124:127], v[16:31]
	v_mfma_f32_32x32x16_bf16 v[16:31], v[112:115], v[128:131], v[16:31]
	s_waitcnt lgkmcnt(0)
	v_fmamk_f32 v80, v80, 0x3dd53b94, v144
	v_fmamk_f32 v81, v81, 0x3dd53b94, v144
	v_exp_f32_e32 v80, v80
	v_fmamk_f32 v82, v82, 0x3dd53b94, v144
	v_exp_f32_e32 v81, v81
	v_fmamk_f32 v83, v83, 0x3dd53b94, v144
	v_exp_f32_e32 v82, v82
	v_fmamk_f32 v84, v84, 0x3dd53b94, v144
	v_fmamk_f32 v64, v64, 0x3dd53b94, v144
	v_exp_f32_e32 v83, v83
	v_mfma_f32_32x32x16_bf16 v[0:15], v[100:103], v[132:135], v[0:15]
	v_fmamk_f32 v85, v85, 0x3dd53b94, v144
	v_exp_f32_e32 v84, v84
	v_exp_f32_e32 v100, v64
	v_add_f32_e32 v64, 0, v80
	v_fmamk_f32 v86, v86, 0x3dd53b94, v144
	v_exp_f32_e32 v85, v85
	v_add_f32_e32 v64, v81, v64
	v_fmamk_f32 v87, v87, 0x3dd53b94, v144
	v_exp_f32_e32 v86, v86
	v_add_f32_e32 v64, v82, v64
	v_fmamk_f32 v88, v88, 0x3dd53b94, v144
	v_exp_f32_e32 v87, v87
	v_add_f32_e32 v64, v83, v64
	v_fmamk_f32 v89, v89, 0x3dd53b94, v144
	v_exp_f32_e32 v88, v88
	v_add_f32_e32 v64, v84, v64
	v_fmamk_f32 v90, v90, 0x3dd53b94, v144
	v_exp_f32_e32 v89, v89
	v_add_f32_e32 v64, v85, v64
	v_fmamk_f32 v91, v91, 0x3dd53b94, v144
	v_exp_f32_e32 v90, v90
	v_add_f32_e32 v64, v86, v64
	v_fmamk_f32 v92, v92, 0x3dd53b94, v144
	v_exp_f32_e32 v91, v91
	v_add_f32_e32 v64, v87, v64
	v_mfma_f32_32x32x16_bf16 v[0:15], v[104:107], v[136:139], v[0:15]
	v_fmamk_f32 v93, v93, 0x3dd53b94, v144
	v_exp_f32_e32 v92, v92
	v_add_f32_e32 v64, v88, v64
	v_fmamk_f32 v94, v94, 0x3dd53b94, v144
	v_exp_f32_e32 v93, v93
	v_add_f32_e32 v64, v89, v64
	v_fmamk_f32 v95, v95, 0x3dd53b94, v144
	v_exp_f32_e32 v94, v94
	v_add_f32_e32 v64, v90, v64
	v_exp_f32_e32 v95, v95
	v_add_f32_e32 v64, v91, v64
	v_fmamk_f32 v65, v65, 0x3dd53b94, v144
	v_add_f32_e32 v64, v92, v64
	v_fmamk_f32 v66, v66, 0x3dd53b94, v144
	v_exp_f32_e32 v101, v65
	v_add_f32_e32 v64, v93, v64
	v_fmamk_f32 v67, v67, 0x3dd53b94, v144
	v_exp_f32_e32 v102, v66
	v_add_f32_e32 v64, v94, v64
	v_fmamk_f32 v68, v68, 0x3dd53b94, v144
	v_exp_f32_e32 v103, v67
	v_add_f32_e32 v64, v95, v64
	v_mfma_f32_32x32x16_bf16 v[0:15], v[108:111], v[140:143], v[0:15]
	v_fmamk_f32 v69, v69, 0x3dd53b94, v144
	v_exp_f32_e32 v104, v68
	v_add_f32_e32 v64, v100, v64
	v_fmamk_f32 v70, v70, 0x3dd53b94, v144
	v_exp_f32_e32 v105, v69
	v_add_f32_e32 v64, v101, v64
	v_fmamk_f32 v71, v71, 0x3dd53b94, v144
	v_exp_f32_e32 v106, v70
	v_add_f32_e32 v64, v102, v64
	v_fmamk_f32 v72, v72, 0x3dd53b94, v144
	v_exp_f32_e32 v107, v71
	v_add_f32_e32 v64, v103, v64
	v_fmamk_f32 v73, v73, 0x3dd53b94, v144
	v_exp_f32_e32 v108, v72
	v_add_f32_e32 v64, v104, v64
	v_fmamk_f32 v74, v74, 0x3dd53b94, v144
	v_exp_f32_e32 v109, v73
	v_add_f32_e32 v64, v105, v64
	v_fmamk_f32 v75, v75, 0x3dd53b94, v144
	v_exp_f32_e32 v110, v74
	v_add_f32_e32 v64, v106, v64
	v_fmamk_f32 v76, v76, 0x3dd53b94, v144
	v_exp_f32_e32 v111, v75
	v_add_f32_e32 v64, v107, v64
	v_mfma_f32_32x32x16_bf16 v[0:15], v[112:115], v[148:151], v[0:15]
	v_fmamk_f32 v77, v77, 0x3dd53b94, v144
	v_exp_f32_e32 v112, v76
	v_add_f32_e32 v64, v108, v64
	v_fmamk_f32 v78, v78, 0x3dd53b94, v144
	v_exp_f32_e32 v113, v77
	v_add_f32_e32 v64, v109, v64
	v_fmamk_f32 v79, v79, 0x3dd53b94, v144
	v_exp_f32_e32 v114, v78
	v_add_f32_e32 v64, v110, v64
	v_exp_f32_e32 v79, v79
	v_add_f32_e32 v64, v111, v64
	v_add_f32_e32 v64, v112, v64
	v_add_f32_e32 v64, v113, v64
	v_add_f32_e32 v64, v114, v64
	v_add_f32_e32 v97, v79, v64
	v_mov_b32_e32 v99, v97
	s_nop 1
	v_permlane32_swap_b32_e32 v97, v99
	v_cvt_pk_bf16_f32 v64, v80, v81
	v_cvt_pk_bf16_f32 v65, v82, v83
	v_cvt_pk_bf16_f32 v66, v84, v85
	v_cvt_pk_bf16_f32 v67, v86, v87
	v_cvt_pk_bf16_f32 v68, v88, v89
	v_cvt_pk_bf16_f32 v69, v90, v91
	v_cvt_pk_bf16_f32 v70, v92, v93
	v_cvt_pk_bf16_f32 v71, v94, v95
	v_cvt_pk_bf16_f32 v72, v100, v101
	v_cvt_pk_bf16_f32 v73, v102, v103
	v_cvt_pk_bf16_f32 v74, v104, v105
	v_cvt_pk_bf16_f32 v75, v106, v107
	v_cvt_pk_bf16_f32 v76, v108, v109
	v_cvt_pk_bf16_f32 v77, v110, v111
	v_cvt_pk_bf16_f32 v78, v112, v113
	v_cvt_pk_bf16_f32 v79, v114, v79
	s_nop 0
	v_permlane32_swap_b32_e32 v64, v66
	v_permlane32_swap_b32_e32 v65, v67
	v_permlane32_swap_b32_e32 v68, v70
	v_permlane32_swap_b32_e32 v69, v71
	v_permlane32_swap_b32_e32 v72, v74
	v_permlane32_swap_b32_e32 v73, v75
	v_permlane32_swap_b32_e32 v76, v78
	v_permlane32_swap_b32_e32 v77, v79
	s_addk_i32 s30, 0x4000
	v_add_u32_e32 v116, s30, v176
	ds_read_b64_tr_b16 v[80:81], v116 offset:0
	ds_read_b64_tr_b16 v[82:83], v116 offset:0x800
	ds_read_b64_tr_b16 v[84:85], v116 offset:0x1000
	ds_read_b64_tr_b16 v[86:87], v116 offset:0x1800
	ds_read_b64_tr_b16 v[88:89], v116 offset:0x2000
	ds_read_b64_tr_b16 v[90:91], v116 offset:0x2800
	ds_read_b64_tr_b16 v[92:93], v116 offset:0x3000
	ds_read_b64_tr_b16 v[94:95], v116 offset:0x3800
	ds_read_b64_tr_b16 v[100:101], v116 offset:0x200
	ds_read_b64_tr_b16 v[102:103], v116 offset:0xa00
	ds_read_b64_tr_b16 v[104:105], v116 offset:0x1200
	ds_read_b64_tr_b16 v[106:107], v116 offset:0x1a00
	ds_read_b64_tr_b16 v[108:109], v116 offset:0x2200
	ds_read_b64_tr_b16 v[110:111], v116 offset:0x2a00
	ds_read_b64_tr_b16 v[112:113], v116 offset:0x3200
	ds_read_b64_tr_b16 v[114:115], v116 offset:0x3a00
	s_waitcnt lgkmcnt(8)
	s_nop 0
	v_mfma_f32_32x32x16_bf16 v[48:63], v[64:67], v[80:83], v[48:63]
	v_mfma_f32_32x32x16_bf16 v[48:63], v[68:71], v[84:87], v[48:63]
	v_mfma_f32_32x32x16_bf16 v[48:63], v[72:75], v[88:91], v[48:63]
	v_mfma_f32_32x32x16_bf16 v[48:63], v[76:79], v[92:95], v[48:63]
	ds_read_b64_tr_b16 v[80:81], v116 offset:0x400
	ds_read_b64_tr_b16 v[82:83], v116 offset:0xc00
	ds_read_b64_tr_b16 v[84:85], v116 offset:0x1400
	ds_read_b64_tr_b16 v[86:87], v116 offset:0x1c00
	ds_read_b64_tr_b16 v[88:89], v116 offset:0x2400
	ds_read_b64_tr_b16 v[90:91], v116 offset:0x2c00
	ds_read_b64_tr_b16 v[92:93], v116 offset:0x3400
	ds_read_b64_tr_b16 v[94:95], v116 offset:0x3c00
	s_waitcnt lgkmcnt(8)
	v_mfma_f32_32x32x16_bf16 v[32:47], v[64:67], v[100:103], v[32:47]
	v_mfma_f32_32x32x16_bf16 v[32:47], v[68:71], v[104:107], v[32:47]
	v_mfma_f32_32x32x16_bf16 v[32:47], v[72:75], v[108:111], v[32:47]
	v_mfma_f32_32x32x16_bf16 v[32:47], v[76:79], v[112:115], v[32:47]
	ds_read_b64_tr_b16 v[100:101], v116 offset:0x600
	ds_read_b64_tr_b16 v[102:103], v116 offset:0xe00
	ds_read_b64_tr_b16 v[104:105], v116 offset:0x1600
	ds_read_b64_tr_b16 v[106:107], v116 offset:0x1e00
	ds_read_b64_tr_b16 v[108:109], v116 offset:0x2600
	ds_read_b64_tr_b16 v[110:111], v116 offset:0x2e00
	ds_read_b64_tr_b16 v[112:113], v116 offset:0x3600
	ds_read_b64_tr_b16 v[114:115], v116 offset:0x3e00
	s_waitcnt lgkmcnt(8)
	v_mfma_f32_32x32x16_bf16 v[16:31], v[64:67], v[80:83], v[16:31]
	v_mfma_f32_32x32x16_bf16 v[16:31], v[68:71], v[84:87], v[16:31]
	v_mfma_f32_32x32x16_bf16 v[16:31], v[72:75], v[88:91], v[16:31]
	v_mfma_f32_32x32x16_bf16 v[16:31], v[76:79], v[92:95], v[16:31]
	s_waitcnt lgkmcnt(0)
	v_mfma_f32_32x32x16_bf16 v[0:15], v[64:67], v[100:103], v[0:15]
	v_cmp_gt_u32_e32 vcc, 32, v200
	v_mfma_f32_32x32x16_bf16 v[0:15], v[68:71], v[104:107], v[0:15]
	v_mfma_f32_32x32x16_bf16 v[0:15], v[72:75], v[108:111], v[0:15]
	v_mfma_f32_32x32x16_bf16 v[0:15], v[76:79], v[112:115], v[0:15]
	s_and_saveexec_b64 s[42:43], vcc
	v_pk_add_f32 v[64:65], v[96:97], v[98:99]
	v_lshl_add_u32 v66, v196, 2, s44
	v_add_f32_e32 v64, v213, v64
	v_add_f32_e32 v64, v64, v65
	ds_write_b32 v66, v64
	s_or_b64 exec, exec, s[42:43]
	s_lshl_b64 s[2:3], s[40:41], 13
	s_or_b64 s[12:13], s[2:3], s[34:35]
	s_mul_i32 s1, s13, 0x3600
	s_mul_hi_u32 s2, s12, 0x3600
	s_add_i32 s1, s2, s1
	s_mul_i32 s14, s12, 0x3600
	s_lshl_b64 s[2:3], s[12:13], 12
	s_lshl_b64 s[12:13], s[12:13], 5
	s_add_u32 s14, s38, s14
	s_addc_u32 s1, s39, s1
	s_add_u32 s15, s72, s2
	s_addc_u32 s30, s73, s3
	s_lshl_b32 s31, s49, 8
	v_lshl_or_b32 v164, v198, 2, s52
	s_add_u32 s2, s14, s31
	s_addc_u32 s3, s1, 0
	s_add_u32 s2, s2, 0x11802c80
	s_addc_u32 s3, s3, 0
	v_subrev_u32_e32 v165, s52, v164
	v_lshl_add_u32 v166, v165, 2, s44
	s_add_u32 s14, s15, s31
	s_addc_u32 s15, s30, 0
	s_add_u32 s1, s74, s12
	s_addc_u32 s12, s75, s13
	s_lshl_b32 s13, s49, 2
	s_add_u32 s42, s1, s13
	s_addc_u32 s43, s12, 0
	v_lshlrev_b32_e32 v167, 1, v196
	v_mul_u32_u24_e32 v168, 0x3600, v164
	v_lshl_add_u32 v169, v164, 12, v167
	v_add_u32_e32 v168, v168, v167
	v_lshlrev_b32_e32 v170, 5, v164
	s_waitcnt lgkmcnt(0)
	ds_read_b32 v128, v166 offset:0
	ds_read_b32 v129, v166 offset:4
	ds_read_b32 v130, v166 offset:8
	ds_read_b32 v131, v166 offset:12
	ds_read_b32 v132, v166 offset:32
	ds_read_b32 v133, v166 offset:36
	ds_read_b32 v134, v166 offset:40
	ds_read_b32 v135, v166 offset:44
	ds_read_b32 v136, v166 offset:64
	ds_read_b32 v137, v166 offset:68
	ds_read_b32 v138, v166 offset:72
	ds_read_b32 v139, v166 offset:76
	ds_read_b32 v140, v166 offset:96
	ds_read_b32 v141, v166 offset:100
	ds_read_b32 v142, v166 offset:104
	ds_read_b32 v143, v166 offset:108
	v_mov_b32_e32 v171, v168
	global_load_ushort v64, v171, s[2:3] offset:0
	global_load_ushort v65, v171, s[2:3] offset:64
	global_load_ushort v66, v171, s[2:3] offset:128
	global_load_ushort v67, v171, s[2:3] offset:192
	v_add_u32_e32 v172, 0x3600, v168
	global_load_ushort v68, v172, s[2:3] offset:0
	global_load_ushort v69, v172, s[2:3] offset:64
	global_load_ushort v70, v172, s[2:3] offset:128
	global_load_ushort v71, v172, s[2:3] offset:192
	v_add_u32_e32 v173, 0x6c00, v168
	global_load_ushort v72, v173, s[2:3] offset:0
	global_load_ushort v73, v173, s[2:3] offset:64
	global_load_ushort v74, v173, s[2:3] offset:128
	global_load_ushort v75, v173, s[2:3] offset:192
	v_add_u32_e32 v174, 0xa200, v168
	global_load_ushort v76, v174, s[2:3] offset:0
	global_load_ushort v77, v174, s[2:3] offset:64
	global_load_ushort v78, v174, s[2:3] offset:128
	global_load_ushort v79, v174, s[2:3] offset:192
	v_add_u32_e32 v171, 0x1b000, v168
	global_load_ushort v80, v171, s[2:3] offset:0
	global_load_ushort v81, v171, s[2:3] offset:64
	global_load_ushort v82, v171, s[2:3] offset:128
	global_load_ushort v83, v171, s[2:3] offset:192
	v_add_u32_e32 v172, 0x1e600, v168
	global_load_ushort v84, v172, s[2:3] offset:0
	global_load_ushort v85, v172, s[2:3] offset:64
	global_load_ushort v86, v172, s[2:3] offset:128
	global_load_ushort v87, v172, s[2:3] offset:192
	v_add_u32_e32 v173, 0x21c00, v168
	global_load_ushort v88, v173, s[2:3] offset:0
	global_load_ushort v89, v173, s[2:3] offset:64
	global_load_ushort v90, v173, s[2:3] offset:128
	global_load_ushort v91, v173, s[2:3] offset:192
	v_add_u32_e32 v174, 0x25200, v168
	global_load_ushort v92, v174, s[2:3] offset:0
	global_load_ushort v93, v174, s[2:3] offset:64
	global_load_ushort v94, v174, s[2:3] offset:128
	global_load_ushort v95, v174, s[2:3] offset:192
	v_add_u32_e32 v171, 0x36000, v168
	global_load_ushort v96, v171, s[2:3] offset:0
	global_load_ushort v97, v171, s[2:3] offset:64
	global_load_ushort v98, v171, s[2:3] offset:128
	global_load_ushort v99, v171, s[2:3] offset:192
	v_add_u32_e32 v172, 0x39600, v168
	global_load_ushort v100, v172, s[2:3] offset:0
	global_load_ushort v101, v172, s[2:3] offset:64
	global_load_ushort v102, v172, s[2:3] offset:128
	global_load_ushort v103, v172, s[2:3] offset:192
	v_add_u32_e32 v173, 0x3cc00, v168
	global_load_ushort v104, v173, s[2:3] offset:0
	global_load_ushort v105, v173, s[2:3] offset:64
	global_load_ushort v106, v173, s[2:3] offset:128
	global_load_ushort v107, v173, s[2:3] offset:192
	v_add_u32_e32 v174, 0x40200, v168
	global_load_ushort v108, v174, s[2:3] offset:0
	global_load_ushort v109, v174, s[2:3] offset:64
	global_load_ushort v110, v174, s[2:3] offset:128
	global_load_ushort v111, v174, s[2:3] offset:192
	v_add_u32_e32 v171, 0x51000, v168
	global_load_ushort v112, v171, s[2:3] offset:0
	global_load_ushort v113, v171, s[2:3] offset:64
	global_load_ushort v114, v171, s[2:3] offset:128
	global_load_ushort v115, v171, s[2:3] offset:192
	v_add_u32_e32 v172, 0x54600, v168
	global_load_ushort v116, v172, s[2:3] offset:0
	global_load_ushort v117, v172, s[2:3] offset:64
	global_load_ushort v118, v172, s[2:3] offset:128
	global_load_ushort v119, v172, s[2:3] offset:192
	v_add_u32_e32 v173, 0x57c00, v168
	global_load_ushort v120, v173, s[2:3] offset:0
	global_load_ushort v121, v173, s[2:3] offset:64
	global_load_ushort v122, v173, s[2:3] offset:128
	global_load_ushort v123, v173, s[2:3] offset:192
	v_add_u32_e32 v174, 0x5b200, v168
	global_load_ushort v124, v174, s[2:3] offset:0
	global_load_ushort v125, v174, s[2:3] offset:64
	global_load_ushort v126, v174, s[2:3] offset:128
	global_load_ushort v127, v174, s[2:3] offset:192
	s_waitcnt lgkmcnt(0)
	v_rcp_f32_e32 v128, v128
	v_rcp_f32_e32 v129, v129
	v_rcp_f32_e32 v130, v130
	v_rcp_f32_e32 v131, v131
	v_rcp_f32_e32 v132, v132
	v_rcp_f32_e32 v133, v133
	v_rcp_f32_e32 v134, v134
	v_rcp_f32_e32 v135, v135
	v_rcp_f32_e32 v136, v136
	v_rcp_f32_e32 v137, v137
	v_rcp_f32_e32 v138, v138
	v_rcp_f32_e32 v139, v139
	v_rcp_f32_e32 v140, v140
	v_rcp_f32_e32 v141, v141
	v_rcp_f32_e32 v142, v142
	v_rcp_f32_e32 v143, v143
	v_mul_f32_e32 v48, v48, v128
	v_mul_f32_e32 v32, v32, v128
	v_mul_f32_e32 v16, v16, v128
	v_mul_f32_e32 v0, v0, v128
	v_mul_f32_e32 v49, v49, v129
	v_mul_f32_e32 v33, v33, v129
	v_mul_f32_e32 v17, v17, v129
	v_mul_f32_e32 v1, v1, v129
	v_mul_f32_e32 v50, v50, v130
	v_mul_f32_e32 v34, v34, v130
	v_mul_f32_e32 v18, v18, v130
	v_mul_f32_e32 v2, v2, v130
	v_mul_f32_e32 v51, v51, v131
	v_mul_f32_e32 v35, v35, v131
	v_mul_f32_e32 v19, v19, v131
	v_mul_f32_e32 v3, v3, v131
	v_mul_f32_e32 v52, v52, v132
	v_mul_f32_e32 v36, v36, v132
	v_mul_f32_e32 v20, v20, v132
	v_mul_f32_e32 v4, v4, v132
	v_mul_f32_e32 v53, v53, v133
	v_mul_f32_e32 v37, v37, v133
	v_mul_f32_e32 v21, v21, v133
	v_mul_f32_e32 v5, v5, v133
	v_mul_f32_e32 v54, v54, v134
	v_mul_f32_e32 v38, v38, v134
	v_mul_f32_e32 v22, v22, v134
	v_mul_f32_e32 v6, v6, v134
	v_mul_f32_e32 v55, v55, v135
	v_mul_f32_e32 v39, v39, v135
	v_mul_f32_e32 v23, v23, v135
	v_mul_f32_e32 v7, v7, v135
	v_mul_f32_e32 v56, v56, v136
	v_mul_f32_e32 v40, v40, v136
	v_mul_f32_e32 v24, v24, v136
	v_mul_f32_e32 v8, v8, v136
	v_mul_f32_e32 v57, v57, v137
	v_mul_f32_e32 v41, v41, v137
	v_mul_f32_e32 v25, v25, v137
	v_mul_f32_e32 v9, v9, v137
	v_mul_f32_e32 v58, v58, v138
	v_mul_f32_e32 v42, v42, v138
	v_mul_f32_e32 v26, v26, v138
	v_mul_f32_e32 v10, v10, v138
	v_mul_f32_e32 v59, v59, v139
	v_mul_f32_e32 v43, v43, v139
	v_mul_f32_e32 v27, v27, v139
	v_mul_f32_e32 v11, v11, v139
	v_mul_f32_e32 v60, v60, v140
	v_mul_f32_e32 v44, v44, v140
	v_mul_f32_e32 v28, v28, v140
	v_mul_f32_e32 v12, v12, v140
	v_mul_f32_e32 v61, v61, v141
	v_mul_f32_e32 v45, v45, v141
	v_mul_f32_e32 v29, v29, v141
	v_mul_f32_e32 v13, v13, v141
	v_mul_f32_e32 v62, v62, v142
	v_mul_f32_e32 v46, v46, v142
	v_mul_f32_e32 v30, v30, v142
	v_mul_f32_e32 v14, v14, v142
	v_mul_f32_e32 v63, v63, v143
	v_mul_f32_e32 v47, v47, v143
	v_mul_f32_e32 v31, v31, v143
	v_mul_f32_e32 v15, v15, v143
	s_waitcnt vmcnt(60)
	v_mov_b32_e32 v182, v169
	v_lshlrev_b32_e32 v64, 16, v64
	v_lshlrev_b32_e32 v65, 16, v65
	v_lshlrev_b32_e32 v66, 16, v66
	v_lshlrev_b32_e32 v67, 16, v67
	v_mul_f32_e32 v208, 0xbfb8aa3b, v64
	v_mul_f32_e32 v214, 0xbfb8aa3b, v65
	v_mul_f32_e32 v220, 0xbfb8aa3b, v66
	v_mul_f32_e32 v226, 0xbfb8aa3b, v67
	v_exp_f32_e32 v208, v208
	v_exp_f32_e32 v214, v214
	v_exp_f32_e32 v220, v220
	v_exp_f32_e32 v226, v226
	v_add_f32_e32 v208, 1.0, v208
	v_add_f32_e32 v214, 1.0, v214
	v_add_f32_e32 v220, 1.0, v220
	v_add_f32_e32 v226, 1.0, v226
	v_div_scale_f32 v209, s[12:13], v208, v208, v64
	v_div_scale_f32 v215, s[12:13], v214, v214, v65
	v_div_scale_f32 v221, s[12:13], v220, v220, v66
	v_div_scale_f32 v227, s[12:13], v226, v226, v67
	v_rcp_f32_e32 v210, v209
	v_rcp_f32_e32 v216, v215
	v_rcp_f32_e32 v222, v221
	v_rcp_f32_e32 v228, v227
	v_fma_f32 v211, -v209, v210, 1.0
	v_fma_f32 v217, -v215, v216, 1.0
	v_fma_f32 v223, -v221, v222, 1.0
	v_fma_f32 v229, -v227, v228, 1.0
	v_fmac_f32_e32 v210, v211, v210
	v_fmac_f32_e32 v216, v217, v216
	v_fmac_f32_e32 v222, v223, v222
	v_fmac_f32_e32 v228, v229, v228
	v_div_scale_f32 v211, vcc, v64, v208, v64
	v_mul_f32_e32 v212, v211, v210
	v_fma_f32 v213, -v209, v212, v211
	v_fmac_f32_e32 v212, v213, v210
	v_fma_f32 v209, -v209, v212, v211
	v_div_fmas_f32 v209, v209, v210, v212
	v_div_fixup_f32 v64, v209, v208, v64
	v_div_scale_f32 v217, vcc, v65, v214, v65
	v_mul_f32_e32 v218, v217, v216
	v_fma_f32 v219, -v215, v218, v217
	v_fmac_f32_e32 v218, v219, v216
	v_fma_f32 v215, -v215, v218, v217
	v_div_fmas_f32 v215, v215, v216, v218
	v_div_fixup_f32 v65, v215, v214, v65
	v_div_scale_f32 v223, vcc, v66, v220, v66
	v_mul_f32_e32 v224, v223, v222
	v_fma_f32 v225, -v221, v224, v223
	v_fmac_f32_e32 v224, v225, v222
	v_fma_f32 v221, -v221, v224, v223
	v_div_fmas_f32 v221, v221, v222, v224
	v_div_fixup_f32 v66, v221, v220, v66
	v_div_scale_f32 v229, vcc, v67, v226, v67
	v_mul_f32_e32 v230, v229, v228
	v_fma_f32 v231, -v227, v230, v229
	v_fmac_f32_e32 v230, v231, v228
	v_fma_f32 v227, -v227, v230, v229
	v_div_fmas_f32 v227, v227, v228, v230
	v_div_fixup_f32 v67, v227, v226, v67
	v_mul_f32_e32 v48, v48, v64
	v_mul_f32_e32 v32, v32, v65
	v_mul_f32_e32 v16, v16, v66
	v_mul_f32_e32 v0, v0, v67
	v_mul_f32_e32 v148, v32, v32
	v_fmac_f32_e32 v148, v48, v48
	v_fmac_f32_e32 v148, v16, v16
	v_fmac_f32_e32 v148, v0, v0
	v_cvt_pk_bf16_f32 v64, v48, v177
	v_cvt_pk_bf16_f32 v65, v32, v177
	v_cvt_pk_bf16_f32 v66, v16, v177
	v_cvt_pk_bf16_f32 v67, v0, v177
	global_store_short v182, v64, s[14:15] offset:0
	global_store_short v182, v65, s[14:15] offset:64
	global_store_short v182, v66, s[14:15] offset:128
	global_store_short v182, v67, s[14:15] offset:192
	s_waitcnt vmcnt(60)
	v_add_u32_e32 v175, 0x1000, v169
	v_lshlrev_b32_e32 v68, 16, v68
	v_lshlrev_b32_e32 v69, 16, v69
	v_lshlrev_b32_e32 v70, 16, v70
	v_lshlrev_b32_e32 v71, 16, v71
	v_mul_f32_e32 v208, 0xbfb8aa3b, v68
	v_mul_f32_e32 v214, 0xbfb8aa3b, v69
	v_mul_f32_e32 v220, 0xbfb8aa3b, v70
	v_mul_f32_e32 v226, 0xbfb8aa3b, v71
	v_exp_f32_e32 v208, v208
	v_exp_f32_e32 v214, v214
	v_exp_f32_e32 v220, v220
	v_exp_f32_e32 v226, v226
	v_add_f32_e32 v208, 1.0, v208
	v_add_f32_e32 v214, 1.0, v214
	v_add_f32_e32 v220, 1.0, v220
	v_add_f32_e32 v226, 1.0, v226
	v_div_scale_f32 v209, s[12:13], v208, v208, v68
	v_div_scale_f32 v215, s[12:13], v214, v214, v69
	v_div_scale_f32 v221, s[12:13], v220, v220, v70
	v_div_scale_f32 v227, s[12:13], v226, v226, v71
	v_rcp_f32_e32 v210, v209
	v_rcp_f32_e32 v216, v215
	v_rcp_f32_e32 v222, v221
	v_rcp_f32_e32 v228, v227
	v_fma_f32 v211, -v209, v210, 1.0
	v_fma_f32 v217, -v215, v216, 1.0
	v_fma_f32 v223, -v221, v222, 1.0
	v_fma_f32 v229, -v227, v228, 1.0
	v_fmac_f32_e32 v210, v211, v210
	v_fmac_f32_e32 v216, v217, v216
	v_fmac_f32_e32 v222, v223, v222
	v_fmac_f32_e32 v228, v229, v228
	v_div_scale_f32 v211, vcc, v68, v208, v68
	v_mul_f32_e32 v212, v211, v210
	v_fma_f32 v213, -v209, v212, v211
	v_fmac_f32_e32 v212, v213, v210
	v_fma_f32 v209, -v209, v212, v211
	v_div_fmas_f32 v209, v209, v210, v212
	v_div_fixup_f32 v68, v209, v208, v68
	v_div_scale_f32 v217, vcc, v69, v214, v69
	v_mul_f32_e32 v218, v217, v216
	v_fma_f32 v219, -v215, v218, v217
	v_fmac_f32_e32 v218, v219, v216
	v_fma_f32 v215, -v215, v218, v217
	v_div_fmas_f32 v215, v215, v216, v218
	v_div_fixup_f32 v69, v215, v214, v69
	v_div_scale_f32 v223, vcc, v70, v220, v70
	v_mul_f32_e32 v224, v223, v222
	v_fma_f32 v225, -v221, v224, v223
	v_fmac_f32_e32 v224, v225, v222
	v_fma_f32 v221, -v221, v224, v223
	v_div_fmas_f32 v221, v221, v222, v224
	v_div_fixup_f32 v70, v221, v220, v70
	v_div_scale_f32 v229, vcc, v71, v226, v71
	v_mul_f32_e32 v230, v229, v228
	v_fma_f32 v231, -v227, v230, v229
	v_fmac_f32_e32 v230, v231, v228
	v_fma_f32 v227, -v227, v230, v229
	v_div_fmas_f32 v227, v227, v228, v230
	v_div_fixup_f32 v71, v227, v226, v71
	v_mul_f32_e32 v49, v49, v68
	v_mul_f32_e32 v33, v33, v69
	v_mul_f32_e32 v17, v17, v70
	v_mul_f32_e32 v1, v1, v71
	v_mul_f32_e32 v149, v33, v33
	v_fmac_f32_e32 v149, v49, v49
	v_fmac_f32_e32 v149, v17, v17
	v_fmac_f32_e32 v149, v1, v1
	v_cvt_pk_bf16_f32 v68, v49, v177
	v_cvt_pk_bf16_f32 v69, v33, v177
	v_cvt_pk_bf16_f32 v70, v17, v177
	v_cvt_pk_bf16_f32 v71, v1, v177
	global_store_short v175, v68, s[14:15] offset:0
	global_store_short v175, v69, s[14:15] offset:64
	global_store_short v175, v70, s[14:15] offset:128
	global_store_short v175, v71, s[14:15] offset:192
	s_waitcnt vmcnt(60)
	v_add_u32_e32 v182, 0x2000, v169
	v_lshlrev_b32_e32 v72, 16, v72
	v_lshlrev_b32_e32 v73, 16, v73
	v_lshlrev_b32_e32 v74, 16, v74
	v_lshlrev_b32_e32 v75, 16, v75
	v_mul_f32_e32 v208, 0xbfb8aa3b, v72
	v_mul_f32_e32 v214, 0xbfb8aa3b, v73
	v_mul_f32_e32 v220, 0xbfb8aa3b, v74
	v_mul_f32_e32 v226, 0xbfb8aa3b, v75
	v_exp_f32_e32 v208, v208
	v_exp_f32_e32 v214, v214
	v_exp_f32_e32 v220, v220
	v_exp_f32_e32 v226, v226
	v_add_f32_e32 v208, 1.0, v208
	v_add_f32_e32 v214, 1.0, v214
	v_add_f32_e32 v220, 1.0, v220
	v_add_f32_e32 v226, 1.0, v226
	v_div_scale_f32 v209, s[12:13], v208, v208, v72
	v_div_scale_f32 v215, s[12:13], v214, v214, v73
	v_div_scale_f32 v221, s[12:13], v220, v220, v74
	v_div_scale_f32 v227, s[12:13], v226, v226, v75
	v_rcp_f32_e32 v210, v209
	v_rcp_f32_e32 v216, v215
	v_rcp_f32_e32 v222, v221
	v_rcp_f32_e32 v228, v227
	v_fma_f32 v211, -v209, v210, 1.0
	v_fma_f32 v217, -v215, v216, 1.0
	v_fma_f32 v223, -v221, v222, 1.0
	v_fma_f32 v229, -v227, v228, 1.0
	v_fmac_f32_e32 v210, v211, v210
	v_fmac_f32_e32 v216, v217, v216
	v_fmac_f32_e32 v222, v223, v222
	v_fmac_f32_e32 v228, v229, v228
	v_div_scale_f32 v211, vcc, v72, v208, v72
	v_mul_f32_e32 v212, v211, v210
	v_fma_f32 v213, -v209, v212, v211
	v_fmac_f32_e32 v212, v213, v210
	v_fma_f32 v209, -v209, v212, v211
	v_div_fmas_f32 v209, v209, v210, v212
	v_div_fixup_f32 v72, v209, v208, v72
	v_div_scale_f32 v217, vcc, v73, v214, v73
	v_mul_f32_e32 v218, v217, v216
	v_fma_f32 v219, -v215, v218, v217
	v_fmac_f32_e32 v218, v219, v216
	v_fma_f32 v215, -v215, v218, v217
	v_div_fmas_f32 v215, v215, v216, v218
	v_div_fixup_f32 v73, v215, v214, v73
	v_div_scale_f32 v223, vcc, v74, v220, v74
	v_mul_f32_e32 v224, v223, v222
	v_fma_f32 v225, -v221, v224, v223
	v_fmac_f32_e32 v224, v225, v222
	v_fma_f32 v221, -v221, v224, v223
	v_div_fmas_f32 v221, v221, v222, v224
	v_div_fixup_f32 v74, v221, v220, v74
	v_div_scale_f32 v229, vcc, v75, v226, v75
	v_mul_f32_e32 v230, v229, v228
	v_fma_f32 v231, -v227, v230, v229
	v_fmac_f32_e32 v230, v231, v228
	v_fma_f32 v227, -v227, v230, v229
	v_div_fmas_f32 v227, v227, v228, v230
	v_div_fixup_f32 v75, v227, v226, v75
	v_mul_f32_e32 v50, v50, v72
	v_mul_f32_e32 v34, v34, v73
	v_mul_f32_e32 v18, v18, v74
	v_mul_f32_e32 v2, v2, v75
	v_mul_f32_e32 v150, v34, v34
	v_fmac_f32_e32 v150, v50, v50
	v_fmac_f32_e32 v150, v18, v18
	v_fmac_f32_e32 v150, v2, v2
	v_cvt_pk_bf16_f32 v72, v50, v177
	v_cvt_pk_bf16_f32 v73, v34, v177
	v_cvt_pk_bf16_f32 v74, v18, v177
	v_cvt_pk_bf16_f32 v75, v2, v177
	global_store_short v182, v72, s[14:15] offset:0
	global_store_short v182, v73, s[14:15] offset:64
	global_store_short v182, v74, s[14:15] offset:128
	global_store_short v182, v75, s[14:15] offset:192
	s_waitcnt vmcnt(60)
	v_add_u32_e32 v175, 0x3000, v169
	v_lshlrev_b32_e32 v76, 16, v76
	v_lshlrev_b32_e32 v77, 16, v77
	v_lshlrev_b32_e32 v78, 16, v78
	v_lshlrev_b32_e32 v79, 16, v79
	v_mul_f32_e32 v208, 0xbfb8aa3b, v76
	v_mul_f32_e32 v214, 0xbfb8aa3b, v77
	v_mul_f32_e32 v220, 0xbfb8aa3b, v78
	v_mul_f32_e32 v226, 0xbfb8aa3b, v79
	v_exp_f32_e32 v208, v208
	v_exp_f32_e32 v214, v214
	v_exp_f32_e32 v220, v220
	v_exp_f32_e32 v226, v226
	v_add_f32_e32 v208, 1.0, v208
	v_add_f32_e32 v214, 1.0, v214
	v_add_f32_e32 v220, 1.0, v220
	v_add_f32_e32 v226, 1.0, v226
	v_div_scale_f32 v209, s[12:13], v208, v208, v76
	v_div_scale_f32 v215, s[12:13], v214, v214, v77
	v_div_scale_f32 v221, s[12:13], v220, v220, v78
	v_div_scale_f32 v227, s[12:13], v226, v226, v79
	v_rcp_f32_e32 v210, v209
	v_rcp_f32_e32 v216, v215
	v_rcp_f32_e32 v222, v221
	v_rcp_f32_e32 v228, v227
	v_fma_f32 v211, -v209, v210, 1.0
	v_fma_f32 v217, -v215, v216, 1.0
	v_fma_f32 v223, -v221, v222, 1.0
	v_fma_f32 v229, -v227, v228, 1.0
	v_fmac_f32_e32 v210, v211, v210
	v_fmac_f32_e32 v216, v217, v216
	v_fmac_f32_e32 v222, v223, v222
	v_fmac_f32_e32 v228, v229, v228
	v_div_scale_f32 v211, vcc, v76, v208, v76
	v_mul_f32_e32 v212, v211, v210
	v_fma_f32 v213, -v209, v212, v211
	v_fmac_f32_e32 v212, v213, v210
	v_fma_f32 v209, -v209, v212, v211
	v_div_fmas_f32 v209, v209, v210, v212
	v_div_fixup_f32 v76, v209, v208, v76
	v_div_scale_f32 v217, vcc, v77, v214, v77
	v_mul_f32_e32 v218, v217, v216
	v_fma_f32 v219, -v215, v218, v217
	v_fmac_f32_e32 v218, v219, v216
	v_fma_f32 v215, -v215, v218, v217
	v_div_fmas_f32 v215, v215, v216, v218
	v_div_fixup_f32 v77, v215, v214, v77
	v_div_scale_f32 v223, vcc, v78, v220, v78
	v_mul_f32_e32 v224, v223, v222
	v_fma_f32 v225, -v221, v224, v223
	v_fmac_f32_e32 v224, v225, v222
	v_fma_f32 v221, -v221, v224, v223
	v_div_fmas_f32 v221, v221, v222, v224
	v_div_fixup_f32 v78, v221, v220, v78
	v_div_scale_f32 v229, vcc, v79, v226, v79
	v_mul_f32_e32 v230, v229, v228
	v_fma_f32 v231, -v227, v230, v229
	v_fmac_f32_e32 v230, v231, v228
	v_fma_f32 v227, -v227, v230, v229
	v_div_fmas_f32 v227, v227, v228, v230
	v_div_fixup_f32 v79, v227, v226, v79
	v_mul_f32_e32 v51, v51, v76
	v_mul_f32_e32 v35, v35, v77
	v_mul_f32_e32 v19, v19, v78
	v_mul_f32_e32 v3, v3, v79
	v_mul_f32_e32 v151, v35, v35
	v_fmac_f32_e32 v151, v51, v51
	v_fmac_f32_e32 v151, v19, v19
	v_fmac_f32_e32 v151, v3, v3
	v_cvt_pk_bf16_f32 v76, v51, v177
	v_cvt_pk_bf16_f32 v77, v35, v177
	v_cvt_pk_bf16_f32 v78, v19, v177
	v_cvt_pk_bf16_f32 v79, v3, v177
	global_store_short v175, v76, s[14:15] offset:0
	global_store_short v175, v77, s[14:15] offset:64
	global_store_short v175, v78, s[14:15] offset:128
	global_store_short v175, v79, s[14:15] offset:192
	s_waitcnt vmcnt(60)
	v_add_u32_e32 v182, 0x8000, v169
	v_lshlrev_b32_e32 v80, 16, v80
	v_lshlrev_b32_e32 v81, 16, v81
	v_lshlrev_b32_e32 v82, 16, v82
	v_lshlrev_b32_e32 v83, 16, v83
	v_mul_f32_e32 v208, 0xbfb8aa3b, v80
	v_mul_f32_e32 v214, 0xbfb8aa3b, v81
	v_mul_f32_e32 v220, 0xbfb8aa3b, v82
	v_mul_f32_e32 v226, 0xbfb8aa3b, v83
	v_exp_f32_e32 v208, v208
	v_exp_f32_e32 v214, v214
	v_exp_f32_e32 v220, v220
	v_exp_f32_e32 v226, v226
	v_add_f32_e32 v208, 1.0, v208
	v_add_f32_e32 v214, 1.0, v214
	v_add_f32_e32 v220, 1.0, v220
	v_add_f32_e32 v226, 1.0, v226
	v_div_scale_f32 v209, s[12:13], v208, v208, v80
	v_div_scale_f32 v215, s[12:13], v214, v214, v81
	v_div_scale_f32 v221, s[12:13], v220, v220, v82
	v_div_scale_f32 v227, s[12:13], v226, v226, v83
	v_rcp_f32_e32 v210, v209
	v_rcp_f32_e32 v216, v215
	v_rcp_f32_e32 v222, v221
	v_rcp_f32_e32 v228, v227
	v_fma_f32 v211, -v209, v210, 1.0
	v_fma_f32 v217, -v215, v216, 1.0
	v_fma_f32 v223, -v221, v222, 1.0
	v_fma_f32 v229, -v227, v228, 1.0
	v_fmac_f32_e32 v210, v211, v210
	v_fmac_f32_e32 v216, v217, v216
	v_fmac_f32_e32 v222, v223, v222
	v_fmac_f32_e32 v228, v229, v228
	v_div_scale_f32 v211, vcc, v80, v208, v80
	v_mul_f32_e32 v212, v211, v210
	v_fma_f32 v213, -v209, v212, v211
	v_fmac_f32_e32 v212, v213, v210
	v_fma_f32 v209, -v209, v212, v211
	v_div_fmas_f32 v209, v209, v210, v212
	v_div_fixup_f32 v80, v209, v208, v80
	v_div_scale_f32 v217, vcc, v81, v214, v81
	v_mul_f32_e32 v218, v217, v216
	v_fma_f32 v219, -v215, v218, v217
	v_fmac_f32_e32 v218, v219, v216
	v_fma_f32 v215, -v215, v218, v217
	v_div_fmas_f32 v215, v215, v216, v218
	v_div_fixup_f32 v81, v215, v214, v81
	v_div_scale_f32 v223, vcc, v82, v220, v82
	v_mul_f32_e32 v224, v223, v222
	v_fma_f32 v225, -v221, v224, v223
	v_fmac_f32_e32 v224, v225, v222
	v_fma_f32 v221, -v221, v224, v223
	v_div_fmas_f32 v221, v221, v222, v224
	v_div_fixup_f32 v82, v221, v220, v82
	v_div_scale_f32 v229, vcc, v83, v226, v83
	v_mul_f32_e32 v230, v229, v228
	v_fma_f32 v231, -v227, v230, v229
	v_fmac_f32_e32 v230, v231, v228
	v_fma_f32 v227, -v227, v230, v229
	v_div_fmas_f32 v227, v227, v228, v230
	v_div_fixup_f32 v83, v227, v226, v83
	v_mul_f32_e32 v52, v52, v80
	v_mul_f32_e32 v36, v36, v81
	v_mul_f32_e32 v20, v20, v82
	v_mul_f32_e32 v4, v4, v83
	v_mul_f32_e32 v152, v36, v36
	v_fmac_f32_e32 v152, v52, v52
	v_fmac_f32_e32 v152, v20, v20
	v_fmac_f32_e32 v152, v4, v4
	v_cvt_pk_bf16_f32 v80, v52, v177
	v_cvt_pk_bf16_f32 v81, v36, v177
	v_cvt_pk_bf16_f32 v82, v20, v177
	v_cvt_pk_bf16_f32 v83, v4, v177
	global_store_short v182, v80, s[14:15] offset:0
	global_store_short v182, v81, s[14:15] offset:64
	global_store_short v182, v82, s[14:15] offset:128
	global_store_short v182, v83, s[14:15] offset:192
	s_waitcnt vmcnt(60)
	v_add_u32_e32 v175, 0x9000, v169
	v_lshlrev_b32_e32 v84, 16, v84
	v_lshlrev_b32_e32 v85, 16, v85
	v_lshlrev_b32_e32 v86, 16, v86
	v_lshlrev_b32_e32 v87, 16, v87
	v_mul_f32_e32 v208, 0xbfb8aa3b, v84
	v_mul_f32_e32 v214, 0xbfb8aa3b, v85
	v_mul_f32_e32 v220, 0xbfb8aa3b, v86
	v_mul_f32_e32 v226, 0xbfb8aa3b, v87
	v_exp_f32_e32 v208, v208
	v_exp_f32_e32 v214, v214
	v_exp_f32_e32 v220, v220
	v_exp_f32_e32 v226, v226
	v_add_f32_e32 v208, 1.0, v208
	v_add_f32_e32 v214, 1.0, v214
	v_add_f32_e32 v220, 1.0, v220
	v_add_f32_e32 v226, 1.0, v226
	v_div_scale_f32 v209, s[12:13], v208, v208, v84
	v_div_scale_f32 v215, s[12:13], v214, v214, v85
	v_div_scale_f32 v221, s[12:13], v220, v220, v86
	v_div_scale_f32 v227, s[12:13], v226, v226, v87
	v_rcp_f32_e32 v210, v209
	v_rcp_f32_e32 v216, v215
	v_rcp_f32_e32 v222, v221
	v_rcp_f32_e32 v228, v227
	v_fma_f32 v211, -v209, v210, 1.0
	v_fma_f32 v217, -v215, v216, 1.0
	v_fma_f32 v223, -v221, v222, 1.0
	v_fma_f32 v229, -v227, v228, 1.0
	v_fmac_f32_e32 v210, v211, v210
	v_fmac_f32_e32 v216, v217, v216
	v_fmac_f32_e32 v222, v223, v222
	v_fmac_f32_e32 v228, v229, v228
	v_div_scale_f32 v211, vcc, v84, v208, v84
	v_mul_f32_e32 v212, v211, v210
	v_fma_f32 v213, -v209, v212, v211
	v_fmac_f32_e32 v212, v213, v210
	v_fma_f32 v209, -v209, v212, v211
	v_div_fmas_f32 v209, v209, v210, v212
	v_div_fixup_f32 v84, v209, v208, v84
	v_div_scale_f32 v217, vcc, v85, v214, v85
	v_mul_f32_e32 v218, v217, v216
	v_fma_f32 v219, -v215, v218, v217
	v_fmac_f32_e32 v218, v219, v216
	v_fma_f32 v215, -v215, v218, v217
	v_div_fmas_f32 v215, v215, v216, v218
	v_div_fixup_f32 v85, v215, v214, v85
	v_div_scale_f32 v223, vcc, v86, v220, v86
	v_mul_f32_e32 v224, v223, v222
	v_fma_f32 v225, -v221, v224, v223
	v_fmac_f32_e32 v224, v225, v222
	v_fma_f32 v221, -v221, v224, v223
	v_div_fmas_f32 v221, v221, v222, v224
	v_div_fixup_f32 v86, v221, v220, v86
	v_div_scale_f32 v229, vcc, v87, v226, v87
	v_mul_f32_e32 v230, v229, v228
	v_fma_f32 v231, -v227, v230, v229
	v_fmac_f32_e32 v230, v231, v228
	v_fma_f32 v227, -v227, v230, v229
	v_div_fmas_f32 v227, v227, v228, v230
	v_div_fixup_f32 v87, v227, v226, v87
	v_mul_f32_e32 v53, v53, v84
	v_mul_f32_e32 v37, v37, v85
	v_mul_f32_e32 v21, v21, v86
	v_mul_f32_e32 v5, v5, v87
	v_mul_f32_e32 v153, v37, v37
	v_fmac_f32_e32 v153, v53, v53
	v_fmac_f32_e32 v153, v21, v21
	v_fmac_f32_e32 v153, v5, v5
	v_cvt_pk_bf16_f32 v84, v53, v177
	v_cvt_pk_bf16_f32 v85, v37, v177
	v_cvt_pk_bf16_f32 v86, v21, v177
	v_cvt_pk_bf16_f32 v87, v5, v177
	global_store_short v175, v84, s[14:15] offset:0
	global_store_short v175, v85, s[14:15] offset:64
	global_store_short v175, v86, s[14:15] offset:128
	global_store_short v175, v87, s[14:15] offset:192
	s_waitcnt vmcnt(60)
	v_add_u32_e32 v182, 0xa000, v169
	v_lshlrev_b32_e32 v88, 16, v88
	v_lshlrev_b32_e32 v89, 16, v89
	v_lshlrev_b32_e32 v90, 16, v90
	v_lshlrev_b32_e32 v91, 16, v91
	v_mul_f32_e32 v208, 0xbfb8aa3b, v88
	v_mul_f32_e32 v214, 0xbfb8aa3b, v89
	v_mul_f32_e32 v220, 0xbfb8aa3b, v90
	v_mul_f32_e32 v226, 0xbfb8aa3b, v91
	v_exp_f32_e32 v208, v208
	v_exp_f32_e32 v214, v214
	v_exp_f32_e32 v220, v220
	v_exp_f32_e32 v226, v226
	v_add_f32_e32 v208, 1.0, v208
	v_add_f32_e32 v214, 1.0, v214
	v_add_f32_e32 v220, 1.0, v220
	v_add_f32_e32 v226, 1.0, v226
	v_div_scale_f32 v209, s[12:13], v208, v208, v88
	v_div_scale_f32 v215, s[12:13], v214, v214, v89
	v_div_scale_f32 v221, s[12:13], v220, v220, v90
	v_div_scale_f32 v227, s[12:13], v226, v226, v91
	v_rcp_f32_e32 v210, v209
	v_rcp_f32_e32 v216, v215
	v_rcp_f32_e32 v222, v221
	v_rcp_f32_e32 v228, v227
	v_fma_f32 v211, -v209, v210, 1.0
	v_fma_f32 v217, -v215, v216, 1.0
	v_fma_f32 v223, -v221, v222, 1.0
	v_fma_f32 v229, -v227, v228, 1.0
	v_fmac_f32_e32 v210, v211, v210
	v_fmac_f32_e32 v216, v217, v216
	v_fmac_f32_e32 v222, v223, v222
	v_fmac_f32_e32 v228, v229, v228
	v_div_scale_f32 v211, vcc, v88, v208, v88
	v_mul_f32_e32 v212, v211, v210
	v_fma_f32 v213, -v209, v212, v211
	v_fmac_f32_e32 v212, v213, v210
	v_fma_f32 v209, -v209, v212, v211
	v_div_fmas_f32 v209, v209, v210, v212
	v_div_fixup_f32 v88, v209, v208, v88
	v_div_scale_f32 v217, vcc, v89, v214, v89
	v_mul_f32_e32 v218, v217, v216
	v_fma_f32 v219, -v215, v218, v217
	v_fmac_f32_e32 v218, v219, v216
	v_fma_f32 v215, -v215, v218, v217
	v_div_fmas_f32 v215, v215, v216, v218
	v_div_fixup_f32 v89, v215, v214, v89
	v_div_scale_f32 v223, vcc, v90, v220, v90
	v_mul_f32_e32 v224, v223, v222
	v_fma_f32 v225, -v221, v224, v223
	v_fmac_f32_e32 v224, v225, v222
	v_fma_f32 v221, -v221, v224, v223
	v_div_fmas_f32 v221, v221, v222, v224
	v_div_fixup_f32 v90, v221, v220, v90
	v_div_scale_f32 v229, vcc, v91, v226, v91
	v_mul_f32_e32 v230, v229, v228
	v_fma_f32 v231, -v227, v230, v229
	v_fmac_f32_e32 v230, v231, v228
	v_fma_f32 v227, -v227, v230, v229
	v_div_fmas_f32 v227, v227, v228, v230
	v_div_fixup_f32 v91, v227, v226, v91
	v_mul_f32_e32 v54, v54, v88
	v_mul_f32_e32 v38, v38, v89
	v_mul_f32_e32 v22, v22, v90
	v_mul_f32_e32 v6, v6, v91
	v_mul_f32_e32 v154, v38, v38
	v_fmac_f32_e32 v154, v54, v54
	v_fmac_f32_e32 v154, v22, v22
	v_fmac_f32_e32 v154, v6, v6
	v_cvt_pk_bf16_f32 v88, v54, v177
	v_cvt_pk_bf16_f32 v89, v38, v177
	v_cvt_pk_bf16_f32 v90, v22, v177
	v_cvt_pk_bf16_f32 v91, v6, v177
	global_store_short v182, v88, s[14:15] offset:0
	global_store_short v182, v89, s[14:15] offset:64
	global_store_short v182, v90, s[14:15] offset:128
	global_store_short v182, v91, s[14:15] offset:192
	s_waitcnt vmcnt(60)
	v_add_u32_e32 v175, 0xb000, v169
	v_lshlrev_b32_e32 v92, 16, v92
	v_lshlrev_b32_e32 v93, 16, v93
	v_lshlrev_b32_e32 v94, 16, v94
	v_lshlrev_b32_e32 v95, 16, v95
	v_mul_f32_e32 v208, 0xbfb8aa3b, v92
	v_mul_f32_e32 v214, 0xbfb8aa3b, v93
	v_mul_f32_e32 v220, 0xbfb8aa3b, v94
	v_mul_f32_e32 v226, 0xbfb8aa3b, v95
	v_exp_f32_e32 v208, v208
	v_exp_f32_e32 v214, v214
	v_exp_f32_e32 v220, v220
	v_exp_f32_e32 v226, v226
	v_add_f32_e32 v208, 1.0, v208
	v_add_f32_e32 v214, 1.0, v214
	v_add_f32_e32 v220, 1.0, v220
	v_add_f32_e32 v226, 1.0, v226
	v_div_scale_f32 v209, s[12:13], v208, v208, v92
	v_div_scale_f32 v215, s[12:13], v214, v214, v93
	v_div_scale_f32 v221, s[12:13], v220, v220, v94
	v_div_scale_f32 v227, s[12:13], v226, v226, v95
	v_rcp_f32_e32 v210, v209
	v_rcp_f32_e32 v216, v215
	v_rcp_f32_e32 v222, v221
	v_rcp_f32_e32 v228, v227
	v_fma_f32 v211, -v209, v210, 1.0
	v_fma_f32 v217, -v215, v216, 1.0
	v_fma_f32 v223, -v221, v222, 1.0
	v_fma_f32 v229, -v227, v228, 1.0
	v_fmac_f32_e32 v210, v211, v210
	v_fmac_f32_e32 v216, v217, v216
	v_fmac_f32_e32 v222, v223, v222
	v_fmac_f32_e32 v228, v229, v228
	v_div_scale_f32 v211, vcc, v92, v208, v92
	v_mul_f32_e32 v212, v211, v210
	v_fma_f32 v213, -v209, v212, v211
	v_fmac_f32_e32 v212, v213, v210
	v_fma_f32 v209, -v209, v212, v211
	v_div_fmas_f32 v209, v209, v210, v212
	v_div_fixup_f32 v92, v209, v208, v92
	v_div_scale_f32 v217, vcc, v93, v214, v93
	v_mul_f32_e32 v218, v217, v216
	v_fma_f32 v219, -v215, v218, v217
	v_fmac_f32_e32 v218, v219, v216
	v_fma_f32 v215, -v215, v218, v217
	v_div_fmas_f32 v215, v215, v216, v218
	v_div_fixup_f32 v93, v215, v214, v93
	v_div_scale_f32 v223, vcc, v94, v220, v94
	v_mul_f32_e32 v224, v223, v222
	v_fma_f32 v225, -v221, v224, v223
	v_fmac_f32_e32 v224, v225, v222
	v_fma_f32 v221, -v221, v224, v223
	v_div_fmas_f32 v221, v221, v222, v224
	v_div_fixup_f32 v94, v221, v220, v94
	v_div_scale_f32 v229, vcc, v95, v226, v95
	v_mul_f32_e32 v230, v229, v228
	v_fma_f32 v231, -v227, v230, v229
	v_fmac_f32_e32 v230, v231, v228
	v_fma_f32 v227, -v227, v230, v229
	v_div_fmas_f32 v227, v227, v228, v230
	v_div_fixup_f32 v95, v227, v226, v95
	v_mul_f32_e32 v55, v55, v92
	v_mul_f32_e32 v39, v39, v93
	v_mul_f32_e32 v23, v23, v94
	v_mul_f32_e32 v7, v7, v95
	v_mul_f32_e32 v155, v39, v39
	v_fmac_f32_e32 v155, v55, v55
	v_fmac_f32_e32 v155, v23, v23
	v_fmac_f32_e32 v155, v7, v7
	v_cvt_pk_bf16_f32 v92, v55, v177
	v_cvt_pk_bf16_f32 v93, v39, v177
	v_cvt_pk_bf16_f32 v94, v23, v177
	v_cvt_pk_bf16_f32 v95, v7, v177
	global_store_short v175, v92, s[14:15] offset:0
	global_store_short v175, v93, s[14:15] offset:64
	global_store_short v175, v94, s[14:15] offset:128
	global_store_short v175, v95, s[14:15] offset:192
	s_waitcnt vmcnt(60)
	v_add_u32_e32 v182, 0x10000, v169
	v_lshlrev_b32_e32 v96, 16, v96
	v_lshlrev_b32_e32 v97, 16, v97
	v_lshlrev_b32_e32 v98, 16, v98
	v_lshlrev_b32_e32 v99, 16, v99
	v_mul_f32_e32 v208, 0xbfb8aa3b, v96
	v_mul_f32_e32 v214, 0xbfb8aa3b, v97
	v_mul_f32_e32 v220, 0xbfb8aa3b, v98
	v_mul_f32_e32 v226, 0xbfb8aa3b, v99
	v_exp_f32_e32 v208, v208
	v_exp_f32_e32 v214, v214
	v_exp_f32_e32 v220, v220
	v_exp_f32_e32 v226, v226
	v_add_f32_e32 v208, 1.0, v208
	v_add_f32_e32 v214, 1.0, v214
	v_add_f32_e32 v220, 1.0, v220
	v_add_f32_e32 v226, 1.0, v226
	v_div_scale_f32 v209, s[12:13], v208, v208, v96
	v_div_scale_f32 v215, s[12:13], v214, v214, v97
	v_div_scale_f32 v221, s[12:13], v220, v220, v98
	v_div_scale_f32 v227, s[12:13], v226, v226, v99
	v_rcp_f32_e32 v210, v209
	v_rcp_f32_e32 v216, v215
	v_rcp_f32_e32 v222, v221
	v_rcp_f32_e32 v228, v227
	v_fma_f32 v211, -v209, v210, 1.0
	v_fma_f32 v217, -v215, v216, 1.0
	v_fma_f32 v223, -v221, v222, 1.0
	v_fma_f32 v229, -v227, v228, 1.0
	v_fmac_f32_e32 v210, v211, v210
	v_fmac_f32_e32 v216, v217, v216
	v_fmac_f32_e32 v222, v223, v222
	v_fmac_f32_e32 v228, v229, v228
	v_div_scale_f32 v211, vcc, v96, v208, v96
	v_mul_f32_e32 v212, v211, v210
	v_fma_f32 v213, -v209, v212, v211
	v_fmac_f32_e32 v212, v213, v210
	v_fma_f32 v209, -v209, v212, v211
	v_div_fmas_f32 v209, v209, v210, v212
	v_div_fixup_f32 v96, v209, v208, v96
	v_div_scale_f32 v217, vcc, v97, v214, v97
	v_mul_f32_e32 v218, v217, v216
	v_fma_f32 v219, -v215, v218, v217
	v_fmac_f32_e32 v218, v219, v216
	v_fma_f32 v215, -v215, v218, v217
	v_div_fmas_f32 v215, v215, v216, v218
	v_div_fixup_f32 v97, v215, v214, v97
	v_div_scale_f32 v223, vcc, v98, v220, v98
	v_mul_f32_e32 v224, v223, v222
	v_fma_f32 v225, -v221, v224, v223
	v_fmac_f32_e32 v224, v225, v222
	v_fma_f32 v221, -v221, v224, v223
	v_div_fmas_f32 v221, v221, v222, v224
	v_div_fixup_f32 v98, v221, v220, v98
	v_div_scale_f32 v229, vcc, v99, v226, v99
	v_mul_f32_e32 v230, v229, v228
	v_fma_f32 v231, -v227, v230, v229
	v_fmac_f32_e32 v230, v231, v228
	v_fma_f32 v227, -v227, v230, v229
	v_div_fmas_f32 v227, v227, v228, v230
	v_div_fixup_f32 v99, v227, v226, v99
	v_mul_f32_e32 v56, v56, v96
	v_mul_f32_e32 v40, v40, v97
	v_mul_f32_e32 v24, v24, v98
	v_mul_f32_e32 v8, v8, v99
	v_mul_f32_e32 v156, v40, v40
	v_fmac_f32_e32 v156, v56, v56
	v_fmac_f32_e32 v156, v24, v24
	v_fmac_f32_e32 v156, v8, v8
	v_cvt_pk_bf16_f32 v96, v56, v177
	v_cvt_pk_bf16_f32 v97, v40, v177
	v_cvt_pk_bf16_f32 v98, v24, v177
	v_cvt_pk_bf16_f32 v99, v8, v177
	global_store_short v182, v96, s[14:15] offset:0
	global_store_short v182, v97, s[14:15] offset:64
	global_store_short v182, v98, s[14:15] offset:128
	global_store_short v182, v99, s[14:15] offset:192
	s_waitcnt vmcnt(60)
	v_add_u32_e32 v175, 0x11000, v169
	v_lshlrev_b32_e32 v100, 16, v100
	v_lshlrev_b32_e32 v101, 16, v101
	v_lshlrev_b32_e32 v102, 16, v102
	v_lshlrev_b32_e32 v103, 16, v103
	v_mul_f32_e32 v208, 0xbfb8aa3b, v100
	v_mul_f32_e32 v214, 0xbfb8aa3b, v101
	v_mul_f32_e32 v220, 0xbfb8aa3b, v102
	v_mul_f32_e32 v226, 0xbfb8aa3b, v103
	v_exp_f32_e32 v208, v208
	v_exp_f32_e32 v214, v214
	v_exp_f32_e32 v220, v220
	v_exp_f32_e32 v226, v226
	v_add_f32_e32 v208, 1.0, v208
	v_add_f32_e32 v214, 1.0, v214
	v_add_f32_e32 v220, 1.0, v220
	v_add_f32_e32 v226, 1.0, v226
	v_div_scale_f32 v209, s[12:13], v208, v208, v100
	v_div_scale_f32 v215, s[12:13], v214, v214, v101
	v_div_scale_f32 v221, s[12:13], v220, v220, v102
	v_div_scale_f32 v227, s[12:13], v226, v226, v103
	v_rcp_f32_e32 v210, v209
	v_rcp_f32_e32 v216, v215
	v_rcp_f32_e32 v222, v221
	v_rcp_f32_e32 v228, v227
	v_fma_f32 v211, -v209, v210, 1.0
	v_fma_f32 v217, -v215, v216, 1.0
	v_fma_f32 v223, -v221, v222, 1.0
	v_fma_f32 v229, -v227, v228, 1.0
	v_fmac_f32_e32 v210, v211, v210
	v_fmac_f32_e32 v216, v217, v216
	v_fmac_f32_e32 v222, v223, v222
	v_fmac_f32_e32 v228, v229, v228
	v_div_scale_f32 v211, vcc, v100, v208, v100
	v_mul_f32_e32 v212, v211, v210
	v_fma_f32 v213, -v209, v212, v211
	v_fmac_f32_e32 v212, v213, v210
	v_fma_f32 v209, -v209, v212, v211
	v_div_fmas_f32 v209, v209, v210, v212
	v_div_fixup_f32 v100, v209, v208, v100
	v_div_scale_f32 v217, vcc, v101, v214, v101
	v_mul_f32_e32 v218, v217, v216
	v_fma_f32 v219, -v215, v218, v217
	v_fmac_f32_e32 v218, v219, v216
	v_fma_f32 v215, -v215, v218, v217
	v_div_fmas_f32 v215, v215, v216, v218
	v_div_fixup_f32 v101, v215, v214, v101
	v_div_scale_f32 v223, vcc, v102, v220, v102
	v_mul_f32_e32 v224, v223, v222
	v_fma_f32 v225, -v221, v224, v223
	v_fmac_f32_e32 v224, v225, v222
	v_fma_f32 v221, -v221, v224, v223
	v_div_fmas_f32 v221, v221, v222, v224
	v_div_fixup_f32 v102, v221, v220, v102
	v_div_scale_f32 v229, vcc, v103, v226, v103
	v_mul_f32_e32 v230, v229, v228
	v_fma_f32 v231, -v227, v230, v229
	v_fmac_f32_e32 v230, v231, v228
	v_fma_f32 v227, -v227, v230, v229
	v_div_fmas_f32 v227, v227, v228, v230
	v_div_fixup_f32 v103, v227, v226, v103
	v_mul_f32_e32 v57, v57, v100
	v_mul_f32_e32 v41, v41, v101
	v_mul_f32_e32 v25, v25, v102
	v_mul_f32_e32 v9, v9, v103
	v_mul_f32_e32 v157, v41, v41
	v_fmac_f32_e32 v157, v57, v57
	v_fmac_f32_e32 v157, v25, v25
	v_fmac_f32_e32 v157, v9, v9
	v_cvt_pk_bf16_f32 v100, v57, v177
	v_cvt_pk_bf16_f32 v101, v41, v177
	v_cvt_pk_bf16_f32 v102, v25, v177
	v_cvt_pk_bf16_f32 v103, v9, v177
	global_store_short v175, v100, s[14:15] offset:0
	global_store_short v175, v101, s[14:15] offset:64
	global_store_short v175, v102, s[14:15] offset:128
	global_store_short v175, v103, s[14:15] offset:192
	s_waitcnt vmcnt(60)
	v_add_u32_e32 v182, 0x12000, v169
	v_lshlrev_b32_e32 v104, 16, v104
	v_lshlrev_b32_e32 v105, 16, v105
	v_lshlrev_b32_e32 v106, 16, v106
	v_lshlrev_b32_e32 v107, 16, v107
	v_mul_f32_e32 v208, 0xbfb8aa3b, v104
	v_mul_f32_e32 v214, 0xbfb8aa3b, v105
	v_mul_f32_e32 v220, 0xbfb8aa3b, v106
	v_mul_f32_e32 v226, 0xbfb8aa3b, v107
	v_exp_f32_e32 v208, v208
	v_exp_f32_e32 v214, v214
	v_exp_f32_e32 v220, v220
	v_exp_f32_e32 v226, v226
	v_add_f32_e32 v208, 1.0, v208
	v_add_f32_e32 v214, 1.0, v214
	v_add_f32_e32 v220, 1.0, v220
	v_add_f32_e32 v226, 1.0, v226
	v_div_scale_f32 v209, s[12:13], v208, v208, v104
	v_div_scale_f32 v215, s[12:13], v214, v214, v105
	v_div_scale_f32 v221, s[12:13], v220, v220, v106
	v_div_scale_f32 v227, s[12:13], v226, v226, v107
	v_rcp_f32_e32 v210, v209
	v_rcp_f32_e32 v216, v215
	v_rcp_f32_e32 v222, v221
	v_rcp_f32_e32 v228, v227
	v_fma_f32 v211, -v209, v210, 1.0
	v_fma_f32 v217, -v215, v216, 1.0
	v_fma_f32 v223, -v221, v222, 1.0
	v_fma_f32 v229, -v227, v228, 1.0
	v_fmac_f32_e32 v210, v211, v210
	v_fmac_f32_e32 v216, v217, v216
	v_fmac_f32_e32 v222, v223, v222
	v_fmac_f32_e32 v228, v229, v228
	v_div_scale_f32 v211, vcc, v104, v208, v104
	v_mul_f32_e32 v212, v211, v210
	v_fma_f32 v213, -v209, v212, v211
	v_fmac_f32_e32 v212, v213, v210
	v_fma_f32 v209, -v209, v212, v211
	v_div_fmas_f32 v209, v209, v210, v212
	v_div_fixup_f32 v104, v209, v208, v104
	v_div_scale_f32 v217, vcc, v105, v214, v105
	v_mul_f32_e32 v218, v217, v216
	v_fma_f32 v219, -v215, v218, v217
	v_fmac_f32_e32 v218, v219, v216
	v_fma_f32 v215, -v215, v218, v217
	v_div_fmas_f32 v215, v215, v216, v218
	v_div_fixup_f32 v105, v215, v214, v105
	v_div_scale_f32 v223, vcc, v106, v220, v106
	v_mul_f32_e32 v224, v223, v222
	v_fma_f32 v225, -v221, v224, v223
	v_fmac_f32_e32 v224, v225, v222
	v_fma_f32 v221, -v221, v224, v223
	v_div_fmas_f32 v221, v221, v222, v224
	v_div_fixup_f32 v106, v221, v220, v106
	v_div_scale_f32 v229, vcc, v107, v226, v107
	v_mul_f32_e32 v230, v229, v228
	v_fma_f32 v231, -v227, v230, v229
	v_fmac_f32_e32 v230, v231, v228
	v_fma_f32 v227, -v227, v230, v229
	v_div_fmas_f32 v227, v227, v228, v230
	v_div_fixup_f32 v107, v227, v226, v107
	v_mul_f32_e32 v58, v58, v104
	v_mul_f32_e32 v42, v42, v105
	v_mul_f32_e32 v26, v26, v106
	v_mul_f32_e32 v10, v10, v107
	v_mul_f32_e32 v158, v42, v42
	v_fmac_f32_e32 v158, v58, v58
	v_fmac_f32_e32 v158, v26, v26
	v_fmac_f32_e32 v158, v10, v10
	v_cvt_pk_bf16_f32 v104, v58, v177
	v_cvt_pk_bf16_f32 v105, v42, v177
	v_cvt_pk_bf16_f32 v106, v26, v177
	v_cvt_pk_bf16_f32 v107, v10, v177
	global_store_short v182, v104, s[14:15] offset:0
	global_store_short v182, v105, s[14:15] offset:64
	global_store_short v182, v106, s[14:15] offset:128
	global_store_short v182, v107, s[14:15] offset:192
	s_waitcnt vmcnt(60)
	v_add_u32_e32 v175, 0x13000, v169
	v_lshlrev_b32_e32 v108, 16, v108
	v_lshlrev_b32_e32 v109, 16, v109
	v_lshlrev_b32_e32 v110, 16, v110
	v_lshlrev_b32_e32 v111, 16, v111
	v_mul_f32_e32 v208, 0xbfb8aa3b, v108
	v_mul_f32_e32 v214, 0xbfb8aa3b, v109
	v_mul_f32_e32 v220, 0xbfb8aa3b, v110
	v_mul_f32_e32 v226, 0xbfb8aa3b, v111
	v_exp_f32_e32 v208, v208
	v_exp_f32_e32 v214, v214
	v_exp_f32_e32 v220, v220
	v_exp_f32_e32 v226, v226
	v_add_f32_e32 v208, 1.0, v208
	v_add_f32_e32 v214, 1.0, v214
	v_add_f32_e32 v220, 1.0, v220
	v_add_f32_e32 v226, 1.0, v226
	v_div_scale_f32 v209, s[12:13], v208, v208, v108
	v_div_scale_f32 v215, s[12:13], v214, v214, v109
	v_div_scale_f32 v221, s[12:13], v220, v220, v110
	v_div_scale_f32 v227, s[12:13], v226, v226, v111
	v_rcp_f32_e32 v210, v209
	v_rcp_f32_e32 v216, v215
	v_rcp_f32_e32 v222, v221
	v_rcp_f32_e32 v228, v227
	v_fma_f32 v211, -v209, v210, 1.0
	v_fma_f32 v217, -v215, v216, 1.0
	v_fma_f32 v223, -v221, v222, 1.0
	v_fma_f32 v229, -v227, v228, 1.0
	v_fmac_f32_e32 v210, v211, v210
	v_fmac_f32_e32 v216, v217, v216
	v_fmac_f32_e32 v222, v223, v222
	v_fmac_f32_e32 v228, v229, v228
	v_div_scale_f32 v211, vcc, v108, v208, v108
	v_mul_f32_e32 v212, v211, v210
	v_fma_f32 v213, -v209, v212, v211
	v_fmac_f32_e32 v212, v213, v210
	v_fma_f32 v209, -v209, v212, v211
	v_div_fmas_f32 v209, v209, v210, v212
	v_div_fixup_f32 v108, v209, v208, v108
	v_div_scale_f32 v217, vcc, v109, v214, v109
	v_mul_f32_e32 v218, v217, v216
	v_fma_f32 v219, -v215, v218, v217
	v_fmac_f32_e32 v218, v219, v216
	v_fma_f32 v215, -v215, v218, v217
	v_div_fmas_f32 v215, v215, v216, v218
	v_div_fixup_f32 v109, v215, v214, v109
	v_div_scale_f32 v223, vcc, v110, v220, v110
	v_mul_f32_e32 v224, v223, v222
	v_fma_f32 v225, -v221, v224, v223
	v_fmac_f32_e32 v224, v225, v222
	v_fma_f32 v221, -v221, v224, v223
	v_div_fmas_f32 v221, v221, v222, v224
	v_div_fixup_f32 v110, v221, v220, v110
	v_div_scale_f32 v229, vcc, v111, v226, v111
	v_mul_f32_e32 v230, v229, v228
	v_fma_f32 v231, -v227, v230, v229
	v_fmac_f32_e32 v230, v231, v228
	v_fma_f32 v227, -v227, v230, v229
	v_div_fmas_f32 v227, v227, v228, v230
	v_div_fixup_f32 v111, v227, v226, v111
	v_mul_f32_e32 v59, v59, v108
	v_mul_f32_e32 v43, v43, v109
	v_mul_f32_e32 v27, v27, v110
	v_mul_f32_e32 v11, v11, v111
	v_mul_f32_e32 v159, v43, v43
	v_fmac_f32_e32 v159, v59, v59
	v_fmac_f32_e32 v159, v27, v27
	v_fmac_f32_e32 v159, v11, v11
	v_cvt_pk_bf16_f32 v108, v59, v177
	v_cvt_pk_bf16_f32 v109, v43, v177
	v_cvt_pk_bf16_f32 v110, v27, v177
	v_cvt_pk_bf16_f32 v111, v11, v177
	global_store_short v175, v108, s[14:15] offset:0
	global_store_short v175, v109, s[14:15] offset:64
	global_store_short v175, v110, s[14:15] offset:128
	global_store_short v175, v111, s[14:15] offset:192
	s_waitcnt vmcnt(60)
	v_add_u32_e32 v182, 0x18000, v169
	v_lshlrev_b32_e32 v112, 16, v112
	v_lshlrev_b32_e32 v113, 16, v113
	v_lshlrev_b32_e32 v114, 16, v114
	v_lshlrev_b32_e32 v115, 16, v115
	v_mul_f32_e32 v208, 0xbfb8aa3b, v112
	v_mul_f32_e32 v214, 0xbfb8aa3b, v113
	v_mul_f32_e32 v220, 0xbfb8aa3b, v114
	v_mul_f32_e32 v226, 0xbfb8aa3b, v115
	v_exp_f32_e32 v208, v208
	v_exp_f32_e32 v214, v214
	v_exp_f32_e32 v220, v220
	v_exp_f32_e32 v226, v226
	v_add_f32_e32 v208, 1.0, v208
	v_add_f32_e32 v214, 1.0, v214
	v_add_f32_e32 v220, 1.0, v220
	v_add_f32_e32 v226, 1.0, v226
	v_div_scale_f32 v209, s[12:13], v208, v208, v112
	v_div_scale_f32 v215, s[12:13], v214, v214, v113
	v_div_scale_f32 v221, s[12:13], v220, v220, v114
	v_div_scale_f32 v227, s[12:13], v226, v226, v115
	v_rcp_f32_e32 v210, v209
	v_rcp_f32_e32 v216, v215
	v_rcp_f32_e32 v222, v221
	v_rcp_f32_e32 v228, v227
	v_fma_f32 v211, -v209, v210, 1.0
	v_fma_f32 v217, -v215, v216, 1.0
	v_fma_f32 v223, -v221, v222, 1.0
	v_fma_f32 v229, -v227, v228, 1.0
	v_fmac_f32_e32 v210, v211, v210
	v_fmac_f32_e32 v216, v217, v216
	v_fmac_f32_e32 v222, v223, v222
	v_fmac_f32_e32 v228, v229, v228
	v_div_scale_f32 v211, vcc, v112, v208, v112
	v_mul_f32_e32 v212, v211, v210
	v_fma_f32 v213, -v209, v212, v211
	v_fmac_f32_e32 v212, v213, v210
	v_fma_f32 v209, -v209, v212, v211
	v_div_fmas_f32 v209, v209, v210, v212
	v_div_fixup_f32 v112, v209, v208, v112
	v_div_scale_f32 v217, vcc, v113, v214, v113
	v_mul_f32_e32 v218, v217, v216
	v_fma_f32 v219, -v215, v218, v217
	v_fmac_f32_e32 v218, v219, v216
	v_fma_f32 v215, -v215, v218, v217
	v_div_fmas_f32 v215, v215, v216, v218
	v_div_fixup_f32 v113, v215, v214, v113
	v_div_scale_f32 v223, vcc, v114, v220, v114
	v_mul_f32_e32 v224, v223, v222
	v_fma_f32 v225, -v221, v224, v223
	v_fmac_f32_e32 v224, v225, v222
	v_fma_f32 v221, -v221, v224, v223
	v_div_fmas_f32 v221, v221, v222, v224
	v_div_fixup_f32 v114, v221, v220, v114
	v_div_scale_f32 v229, vcc, v115, v226, v115
	v_mul_f32_e32 v230, v229, v228
	v_fma_f32 v231, -v227, v230, v229
	v_fmac_f32_e32 v230, v231, v228
	v_fma_f32 v227, -v227, v230, v229
	v_div_fmas_f32 v227, v227, v228, v230
	v_div_fixup_f32 v115, v227, v226, v115
	v_mul_f32_e32 v60, v60, v112
	v_mul_f32_e32 v44, v44, v113
	v_mul_f32_e32 v28, v28, v114
	v_mul_f32_e32 v12, v12, v115
	v_mul_f32_e32 v160, v44, v44
	v_fmac_f32_e32 v160, v60, v60
	v_fmac_f32_e32 v160, v28, v28
	v_fmac_f32_e32 v160, v12, v12
	v_cvt_pk_bf16_f32 v112, v60, v177
	v_cvt_pk_bf16_f32 v113, v44, v177
	v_cvt_pk_bf16_f32 v114, v28, v177
	v_cvt_pk_bf16_f32 v115, v12, v177
	global_store_short v182, v112, s[14:15] offset:0
	global_store_short v182, v113, s[14:15] offset:64
	global_store_short v182, v114, s[14:15] offset:128
	global_store_short v182, v115, s[14:15] offset:192
	s_waitcnt vmcnt(60)
	v_add_u32_e32 v175, 0x19000, v169
	v_lshlrev_b32_e32 v116, 16, v116
	v_lshlrev_b32_e32 v117, 16, v117
	v_lshlrev_b32_e32 v118, 16, v118
	v_lshlrev_b32_e32 v119, 16, v119
	v_mul_f32_e32 v208, 0xbfb8aa3b, v116
	v_mul_f32_e32 v214, 0xbfb8aa3b, v117
	v_mul_f32_e32 v220, 0xbfb8aa3b, v118
	v_mul_f32_e32 v226, 0xbfb8aa3b, v119
	v_exp_f32_e32 v208, v208
	v_exp_f32_e32 v214, v214
	v_exp_f32_e32 v220, v220
	v_exp_f32_e32 v226, v226
	v_add_f32_e32 v208, 1.0, v208
	v_add_f32_e32 v214, 1.0, v214
	v_add_f32_e32 v220, 1.0, v220
	v_add_f32_e32 v226, 1.0, v226
	v_div_scale_f32 v209, s[12:13], v208, v208, v116
	v_div_scale_f32 v215, s[12:13], v214, v214, v117
	v_div_scale_f32 v221, s[12:13], v220, v220, v118
	v_div_scale_f32 v227, s[12:13], v226, v226, v119
	v_rcp_f32_e32 v210, v209
	v_rcp_f32_e32 v216, v215
	v_rcp_f32_e32 v222, v221
	v_rcp_f32_e32 v228, v227
	v_fma_f32 v211, -v209, v210, 1.0
	v_fma_f32 v217, -v215, v216, 1.0
	v_fma_f32 v223, -v221, v222, 1.0
	v_fma_f32 v229, -v227, v228, 1.0
	v_fmac_f32_e32 v210, v211, v210
	v_fmac_f32_e32 v216, v217, v216
	v_fmac_f32_e32 v222, v223, v222
	v_fmac_f32_e32 v228, v229, v228
	v_div_scale_f32 v211, vcc, v116, v208, v116
	v_mul_f32_e32 v212, v211, v210
	v_fma_f32 v213, -v209, v212, v211
	v_fmac_f32_e32 v212, v213, v210
	v_fma_f32 v209, -v209, v212, v211
	v_div_fmas_f32 v209, v209, v210, v212
	v_div_fixup_f32 v116, v209, v208, v116
	v_div_scale_f32 v217, vcc, v117, v214, v117
	v_mul_f32_e32 v218, v217, v216
	v_fma_f32 v219, -v215, v218, v217
	v_fmac_f32_e32 v218, v219, v216
	v_fma_f32 v215, -v215, v218, v217
	v_div_fmas_f32 v215, v215, v216, v218
	v_div_fixup_f32 v117, v215, v214, v117
	v_div_scale_f32 v223, vcc, v118, v220, v118
	v_mul_f32_e32 v224, v223, v222
	v_fma_f32 v225, -v221, v224, v223
	v_fmac_f32_e32 v224, v225, v222
	v_fma_f32 v221, -v221, v224, v223
	v_div_fmas_f32 v221, v221, v222, v224
	v_div_fixup_f32 v118, v221, v220, v118
	v_div_scale_f32 v229, vcc, v119, v226, v119
	v_mul_f32_e32 v230, v229, v228
	v_fma_f32 v231, -v227, v230, v229
	v_fmac_f32_e32 v230, v231, v228
	v_fma_f32 v227, -v227, v230, v229
	v_div_fmas_f32 v227, v227, v228, v230
	v_div_fixup_f32 v119, v227, v226, v119
	v_mul_f32_e32 v61, v61, v116
	v_mul_f32_e32 v45, v45, v117
	v_mul_f32_e32 v29, v29, v118
	v_mul_f32_e32 v13, v13, v119
	v_mul_f32_e32 v161, v45, v45
	v_fmac_f32_e32 v161, v61, v61
	v_fmac_f32_e32 v161, v29, v29
	v_fmac_f32_e32 v161, v13, v13
	v_cvt_pk_bf16_f32 v116, v61, v177
	v_cvt_pk_bf16_f32 v117, v45, v177
	v_cvt_pk_bf16_f32 v118, v29, v177
	v_cvt_pk_bf16_f32 v119, v13, v177
	global_store_short v175, v116, s[14:15] offset:0
	global_store_short v175, v117, s[14:15] offset:64
	global_store_short v175, v118, s[14:15] offset:128
	global_store_short v175, v119, s[14:15] offset:192
	s_waitcnt vmcnt(60)
	v_add_u32_e32 v182, 0x1a000, v169
	v_lshlrev_b32_e32 v120, 16, v120
	v_lshlrev_b32_e32 v121, 16, v121
	v_lshlrev_b32_e32 v122, 16, v122
	v_lshlrev_b32_e32 v123, 16, v123
	v_mul_f32_e32 v208, 0xbfb8aa3b, v120
	v_mul_f32_e32 v214, 0xbfb8aa3b, v121
	v_mul_f32_e32 v220, 0xbfb8aa3b, v122
	v_mul_f32_e32 v226, 0xbfb8aa3b, v123
	v_exp_f32_e32 v208, v208
	v_exp_f32_e32 v214, v214
	v_exp_f32_e32 v220, v220
	v_exp_f32_e32 v226, v226
	v_add_f32_e32 v208, 1.0, v208
	v_add_f32_e32 v214, 1.0, v214
	v_add_f32_e32 v220, 1.0, v220
	v_add_f32_e32 v226, 1.0, v226
	v_div_scale_f32 v209, s[12:13], v208, v208, v120
	v_div_scale_f32 v215, s[12:13], v214, v214, v121
	v_div_scale_f32 v221, s[12:13], v220, v220, v122
	v_div_scale_f32 v227, s[12:13], v226, v226, v123
	v_rcp_f32_e32 v210, v209
	v_rcp_f32_e32 v216, v215
	v_rcp_f32_e32 v222, v221
	v_rcp_f32_e32 v228, v227
	v_fma_f32 v211, -v209, v210, 1.0
	v_fma_f32 v217, -v215, v216, 1.0
	v_fma_f32 v223, -v221, v222, 1.0
	v_fma_f32 v229, -v227, v228, 1.0
	v_fmac_f32_e32 v210, v211, v210
	v_fmac_f32_e32 v216, v217, v216
	v_fmac_f32_e32 v222, v223, v222
	v_fmac_f32_e32 v228, v229, v228
	v_div_scale_f32 v211, vcc, v120, v208, v120
	v_mul_f32_e32 v212, v211, v210
	v_fma_f32 v213, -v209, v212, v211
	v_fmac_f32_e32 v212, v213, v210
	v_fma_f32 v209, -v209, v212, v211
	v_div_fmas_f32 v209, v209, v210, v212
	v_div_fixup_f32 v120, v209, v208, v120
	v_div_scale_f32 v217, vcc, v121, v214, v121
	v_mul_f32_e32 v218, v217, v216
	v_fma_f32 v219, -v215, v218, v217
	v_fmac_f32_e32 v218, v219, v216
	v_fma_f32 v215, -v215, v218, v217
	v_div_fmas_f32 v215, v215, v216, v218
	v_div_fixup_f32 v121, v215, v214, v121
	v_div_scale_f32 v223, vcc, v122, v220, v122
	v_mul_f32_e32 v224, v223, v222
	v_fma_f32 v225, -v221, v224, v223
	v_fmac_f32_e32 v224, v225, v222
	v_fma_f32 v221, -v221, v224, v223
	v_div_fmas_f32 v221, v221, v222, v224
	v_div_fixup_f32 v122, v221, v220, v122
	v_div_scale_f32 v229, vcc, v123, v226, v123
	v_mul_f32_e32 v230, v229, v228
	v_fma_f32 v231, -v227, v230, v229
	v_fmac_f32_e32 v230, v231, v228
	v_fma_f32 v227, -v227, v230, v229
	v_div_fmas_f32 v227, v227, v228, v230
	v_div_fixup_f32 v123, v227, v226, v123
	v_mul_f32_e32 v62, v62, v120
	v_mul_f32_e32 v46, v46, v121
	v_mul_f32_e32 v30, v30, v122
	v_mul_f32_e32 v14, v14, v123
	v_mul_f32_e32 v162, v46, v46
	v_fmac_f32_e32 v162, v62, v62
	v_fmac_f32_e32 v162, v30, v30
	v_fmac_f32_e32 v162, v14, v14
	v_cvt_pk_bf16_f32 v120, v62, v177
	v_cvt_pk_bf16_f32 v121, v46, v177
	v_cvt_pk_bf16_f32 v122, v30, v177
	v_cvt_pk_bf16_f32 v123, v14, v177
	global_store_short v182, v120, s[14:15] offset:0
	global_store_short v182, v121, s[14:15] offset:64
	global_store_short v182, v122, s[14:15] offset:128
	global_store_short v182, v123, s[14:15] offset:192
	s_waitcnt vmcnt(60)
	v_add_u32_e32 v175, 0x1b000, v169
	v_lshlrev_b32_e32 v124, 16, v124
	v_lshlrev_b32_e32 v125, 16, v125
	v_lshlrev_b32_e32 v126, 16, v126
	v_lshlrev_b32_e32 v127, 16, v127
	v_mul_f32_e32 v208, 0xbfb8aa3b, v124
	v_mul_f32_e32 v214, 0xbfb8aa3b, v125
	v_mul_f32_e32 v220, 0xbfb8aa3b, v126
	v_mul_f32_e32 v226, 0xbfb8aa3b, v127
	v_exp_f32_e32 v208, v208
	v_exp_f32_e32 v214, v214
	v_exp_f32_e32 v220, v220
	v_exp_f32_e32 v226, v226
	v_add_f32_e32 v208, 1.0, v208
	v_add_f32_e32 v214, 1.0, v214
	v_add_f32_e32 v220, 1.0, v220
	v_add_f32_e32 v226, 1.0, v226
	v_div_scale_f32 v209, s[12:13], v208, v208, v124
	v_div_scale_f32 v215, s[12:13], v214, v214, v125
	v_div_scale_f32 v221, s[12:13], v220, v220, v126
	v_div_scale_f32 v227, s[12:13], v226, v226, v127
	v_rcp_f32_e32 v210, v209
	v_rcp_f32_e32 v216, v215
	v_rcp_f32_e32 v222, v221
	v_rcp_f32_e32 v228, v227
	v_fma_f32 v211, -v209, v210, 1.0
	v_fma_f32 v217, -v215, v216, 1.0
	v_fma_f32 v223, -v221, v222, 1.0
	v_fma_f32 v229, -v227, v228, 1.0
	v_fmac_f32_e32 v210, v211, v210
	v_fmac_f32_e32 v216, v217, v216
	v_fmac_f32_e32 v222, v223, v222
	v_fmac_f32_e32 v228, v229, v228
	v_div_scale_f32 v211, vcc, v124, v208, v124
	v_mul_f32_e32 v212, v211, v210
	v_fma_f32 v213, -v209, v212, v211
	v_fmac_f32_e32 v212, v213, v210
	v_fma_f32 v209, -v209, v212, v211
	v_div_fmas_f32 v209, v209, v210, v212
	v_div_fixup_f32 v124, v209, v208, v124
	v_div_scale_f32 v217, vcc, v125, v214, v125
	v_mul_f32_e32 v218, v217, v216
	v_fma_f32 v219, -v215, v218, v217
	v_fmac_f32_e32 v218, v219, v216
	v_fma_f32 v215, -v215, v218, v217
	v_div_fmas_f32 v215, v215, v216, v218
	v_div_fixup_f32 v125, v215, v214, v125
	v_div_scale_f32 v223, vcc, v126, v220, v126
	v_mul_f32_e32 v224, v223, v222
	v_fma_f32 v225, -v221, v224, v223
	v_fmac_f32_e32 v224, v225, v222
	v_fma_f32 v221, -v221, v224, v223
	v_div_fmas_f32 v221, v221, v222, v224
	v_div_fixup_f32 v126, v221, v220, v126
	v_div_scale_f32 v229, vcc, v127, v226, v127
	v_mul_f32_e32 v230, v229, v228
	v_fma_f32 v231, -v227, v230, v229
	v_fmac_f32_e32 v230, v231, v228
	v_fma_f32 v227, -v227, v230, v229
	v_div_fmas_f32 v227, v227, v228, v230
	v_div_fixup_f32 v127, v227, v226, v127
	v_mul_f32_e32 v63, v63, v124
	v_mul_f32_e32 v47, v47, v125
	v_mul_f32_e32 v31, v31, v126
	v_mul_f32_e32 v15, v15, v127
	v_mul_f32_e32 v163, v47, v47
	v_fmac_f32_e32 v163, v63, v63
	v_fmac_f32_e32 v163, v31, v31
	v_fmac_f32_e32 v163, v15, v15
	v_cvt_pk_bf16_f32 v124, v63, v177
	v_cvt_pk_bf16_f32 v125, v47, v177
	v_cvt_pk_bf16_f32 v126, v31, v177
	v_cvt_pk_bf16_f32 v127, v15, v177
	global_store_short v175, v124, s[14:15] offset:0
	global_store_short v175, v125, s[14:15] offset:64
	global_store_short v175, v126, s[14:15] offset:128
	global_store_short v175, v127, s[14:15] offset:192
	v_add_f32_dpp v148, v148, v148 quad_perm:[1,0,3,2] row_mask:0xf bank_mask:0xf
	v_add_f32_dpp v149, v149, v149 quad_perm:[1,0,3,2] row_mask:0xf bank_mask:0xf
	v_add_f32_dpp v150, v150, v150 quad_perm:[1,0,3,2] row_mask:0xf bank_mask:0xf
	v_add_f32_dpp v151, v151, v151 quad_perm:[1,0,3,2] row_mask:0xf bank_mask:0xf
	v_add_f32_dpp v152, v152, v152 quad_perm:[1,0,3,2] row_mask:0xf bank_mask:0xf
	v_add_f32_dpp v153, v153, v153 quad_perm:[1,0,3,2] row_mask:0xf bank_mask:0xf
	v_add_f32_dpp v154, v154, v154 quad_perm:[1,0,3,2] row_mask:0xf bank_mask:0xf
	v_add_f32_dpp v155, v155, v155 quad_perm:[1,0,3,2] row_mask:0xf bank_mask:0xf
	v_add_f32_dpp v156, v156, v156 quad_perm:[1,0,3,2] row_mask:0xf bank_mask:0xf
	v_add_f32_dpp v157, v157, v157 quad_perm:[1,0,3,2] row_mask:0xf bank_mask:0xf
	v_add_f32_dpp v158, v158, v158 quad_perm:[1,0,3,2] row_mask:0xf bank_mask:0xf
	v_add_f32_dpp v159, v159, v159 quad_perm:[1,0,3,2] row_mask:0xf bank_mask:0xf
	v_add_f32_dpp v160, v160, v160 quad_perm:[1,0,3,2] row_mask:0xf bank_mask:0xf
	v_add_f32_dpp v161, v161, v161 quad_perm:[1,0,3,2] row_mask:0xf bank_mask:0xf
	v_add_f32_dpp v162, v162, v162 quad_perm:[1,0,3,2] row_mask:0xf bank_mask:0xf
	v_add_f32_dpp v163, v163, v163 quad_perm:[1,0,3,2] row_mask:0xf bank_mask:0xf
	v_add_f32_dpp v148, v148, v148 quad_perm:[2,3,0,1] row_mask:0xf bank_mask:0xf
	v_add_f32_dpp v149, v149, v149 quad_perm:[2,3,0,1] row_mask:0xf bank_mask:0xf
	v_add_f32_dpp v150, v150, v150 quad_perm:[2,3,0,1] row_mask:0xf bank_mask:0xf
	v_add_f32_dpp v151, v151, v151 quad_perm:[2,3,0,1] row_mask:0xf bank_mask:0xf
	v_add_f32_dpp v152, v152, v152 quad_perm:[2,3,0,1] row_mask:0xf bank_mask:0xf
	v_add_f32_dpp v153, v153, v153 quad_perm:[2,3,0,1] row_mask:0xf bank_mask:0xf
	v_add_f32_dpp v154, v154, v154 quad_perm:[2,3,0,1] row_mask:0xf bank_mask:0xf
	v_add_f32_dpp v155, v155, v155 quad_perm:[2,3,0,1] row_mask:0xf bank_mask:0xf
	v_add_f32_dpp v156, v156, v156 quad_perm:[2,3,0,1] row_mask:0xf bank_mask:0xf
	v_add_f32_dpp v157, v157, v157 quad_perm:[2,3,0,1] row_mask:0xf bank_mask:0xf
	v_add_f32_dpp v158, v158, v158 quad_perm:[2,3,0,1] row_mask:0xf bank_mask:0xf
	v_add_f32_dpp v159, v159, v159 quad_perm:[2,3,0,1] row_mask:0xf bank_mask:0xf
	v_add_f32_dpp v160, v160, v160 quad_perm:[2,3,0,1] row_mask:0xf bank_mask:0xf
	v_add_f32_dpp v161, v161, v161 quad_perm:[2,3,0,1] row_mask:0xf bank_mask:0xf
	v_add_f32_dpp v162, v162, v162 quad_perm:[2,3,0,1] row_mask:0xf bank_mask:0xf
	v_add_f32_dpp v163, v163, v163 quad_perm:[2,3,0,1] row_mask:0xf bank_mask:0xf
	v_add_f32_dpp v148, v148, v148 row_half_mirror row_mask:0xf bank_mask:0xf
	v_add_f32_dpp v149, v149, v149 row_half_mirror row_mask:0xf bank_mask:0xf
	v_add_f32_dpp v150, v150, v150 row_half_mirror row_mask:0xf bank_mask:0xf
	v_add_f32_dpp v151, v151, v151 row_half_mirror row_mask:0xf bank_mask:0xf
	v_add_f32_dpp v152, v152, v152 row_half_mirror row_mask:0xf bank_mask:0xf
	v_add_f32_dpp v153, v153, v153 row_half_mirror row_mask:0xf bank_mask:0xf
	v_add_f32_dpp v154, v154, v154 row_half_mirror row_mask:0xf bank_mask:0xf
	v_add_f32_dpp v155, v155, v155 row_half_mirror row_mask:0xf bank_mask:0xf
	v_add_f32_dpp v156, v156, v156 row_half_mirror row_mask:0xf bank_mask:0xf
	v_add_f32_dpp v157, v157, v157 row_half_mirror row_mask:0xf bank_mask:0xf
	v_add_f32_dpp v158, v158, v158 row_half_mirror row_mask:0xf bank_mask:0xf
	v_add_f32_dpp v159, v159, v159 row_half_mirror row_mask:0xf bank_mask:0xf
	v_add_f32_dpp v160, v160, v160 row_half_mirror row_mask:0xf bank_mask:0xf
	v_add_f32_dpp v161, v161, v161 row_half_mirror row_mask:0xf bank_mask:0xf
	v_add_f32_dpp v162, v162, v162 row_half_mirror row_mask:0xf bank_mask:0xf
	v_add_f32_dpp v163, v163, v163 row_half_mirror row_mask:0xf bank_mask:0xf
	v_add_f32_dpp v148, v148, v148 row_mirror row_mask:0xf bank_mask:0xf
	v_add_f32_dpp v149, v149, v149 row_mirror row_mask:0xf bank_mask:0xf
	v_add_f32_dpp v150, v150, v150 row_mirror row_mask:0xf bank_mask:0xf
	v_add_f32_dpp v151, v151, v151 row_mirror row_mask:0xf bank_mask:0xf
	v_add_f32_dpp v152, v152, v152 row_mirror row_mask:0xf bank_mask:0xf
	v_add_f32_dpp v153, v153, v153 row_mirror row_mask:0xf bank_mask:0xf
	v_add_f32_dpp v154, v154, v154 row_mirror row_mask:0xf bank_mask:0xf
	v_add_f32_dpp v155, v155, v155 row_mirror row_mask:0xf bank_mask:0xf
	v_add_f32_dpp v156, v156, v156 row_mirror row_mask:0xf bank_mask:0xf
	v_add_f32_dpp v157, v157, v157 row_mirror row_mask:0xf bank_mask:0xf
	v_add_f32_dpp v158, v158, v158 row_mirror row_mask:0xf bank_mask:0xf
	v_add_f32_dpp v159, v159, v159 row_mirror row_mask:0xf bank_mask:0xf
	v_add_f32_dpp v160, v160, v160 row_mirror row_mask:0xf bank_mask:0xf
	v_add_f32_dpp v161, v161, v161 row_mirror row_mask:0xf bank_mask:0xf
	v_add_f32_dpp v162, v162, v162 row_mirror row_mask:0xf bank_mask:0xf
	v_add_f32_dpp v163, v163, v163 row_mirror row_mask:0xf bank_mask:0xf
	ds_bpermute_b32 v208, v207, v148
	ds_bpermute_b32 v209, v207, v149
	ds_bpermute_b32 v210, v207, v150
	ds_bpermute_b32 v211, v207, v151
	ds_bpermute_b32 v212, v207, v152
	ds_bpermute_b32 v213, v207, v153
	ds_bpermute_b32 v214, v207, v154
	ds_bpermute_b32 v215, v207, v155
	ds_bpermute_b32 v216, v207, v156
	ds_bpermute_b32 v217, v207, v157
	ds_bpermute_b32 v218, v207, v158
	ds_bpermute_b32 v219, v207, v159
	ds_bpermute_b32 v220, v207, v160
	ds_bpermute_b32 v221, v207, v161
	ds_bpermute_b32 v222, v207, v162
	ds_bpermute_b32 v223, v207, v163
	v_cmp_eq_u32_e64 s[40:41], 0, v196
	s_waitcnt lgkmcnt(0)
	v_add_f32_e32 v148, v148, v208
	v_add_f32_e32 v149, v149, v209
	v_add_f32_e32 v150, v150, v210
	v_add_f32_e32 v151, v151, v211
	v_add_f32_e32 v152, v152, v212
	v_add_f32_e32 v153, v153, v213
	v_add_f32_e32 v154, v154, v214
	v_add_f32_e32 v155, v155, v215
	v_add_f32_e32 v156, v156, v216
	v_add_f32_e32 v157, v157, v217
	v_add_f32_e32 v158, v158, v218
	v_add_f32_e32 v159, v159, v219
	v_add_f32_e32 v160, v160, v220
	v_add_f32_e32 v161, v161, v221
	v_add_f32_e32 v162, v162, v222
	v_add_f32_e32 v163, v163, v223
	s_and_saveexec_b64 s[44:45], s[40:41]
	v_mov_b32_e32 v171, v170
	global_store_dword v171, v148, s[42:43]
	v_add_u32_e32 v172, 0x20, v170
	global_store_dword v172, v149, s[42:43]
	v_add_u32_e32 v173, 0x40, v170
	global_store_dword v173, v150, s[42:43]
	v_add_u32_e32 v174, 0x60, v170
	global_store_dword v174, v151, s[42:43]
	v_add_u32_e32 v171, 0x100, v170
	global_store_dword v171, v152, s[42:43]
	v_add_u32_e32 v172, 0x120, v170
	global_store_dword v172, v153, s[42:43]
	v_add_u32_e32 v173, 0x140, v170
	global_store_dword v173, v154, s[42:43]
	v_add_u32_e32 v174, 0x160, v170
	global_store_dword v174, v155, s[42:43]
	v_add_u32_e32 v171, 0x200, v170
	global_store_dword v171, v156, s[42:43]
	v_add_u32_e32 v172, 0x220, v170
	global_store_dword v172, v157, s[42:43]
	v_add_u32_e32 v173, 0x240, v170
	global_store_dword v173, v158, s[42:43]
	v_add_u32_e32 v174, 0x260, v170
	global_store_dword v174, v159, s[42:43]
	v_add_u32_e32 v171, 0x300, v170
	global_store_dword v171, v160, s[42:43]
	v_add_u32_e32 v172, 0x320, v170
	global_store_dword v172, v161, s[42:43]
	v_add_u32_e32 v173, 0x340, v170
	global_store_dword v173, v162, s[42:43]
	v_add_u32_e32 v174, 0x360, v170
	global_store_dword v174, v163, s[42:43]
	s_or_b64 exec, exec, s[44:45]
	s_branch .LBB0_416
